# noprio + write-through (sc1) stores in the IN-projection epilogue
# baseline (speedup 1.0000x reference)
; #define LAS __attribute__((address_space(3)))
; __device__ __forceinline__ unsigned cvtpk_h(float lo, float hi) { f32x2 v = {lo, hi}; h16x2 b = __builtin_convertvector(v, h16x2); return __builtin_bit_cast(unsigned, b); }
;     __device__ __forceinline__ void operator()(const f32x4 (&acc)[2][2][4][2], const pg8::Unit& u, int wr, int wc, int fr, int fq) const {
;     ...
;         for (int ai = 0; ai < 2; ++ai)
; #pragma unroll
;             for (int m = 0; m < 4; ++m) { const float r = rs[ai][m]; f32x4 v[2][2]; float ss = 0.f;
; #pragma unroll
;                 for (int bj = 0; bj < 2; ++bj)
; #pragma unroll
;                     for (int n = 0; n < 2; ++n) { v[bj][n] = acc[ai][bj][m][n] * r + bv[bj][n]; ss += (v[bj][n][0] * v[bj][n][0] + v[bj][n][1] * v[bj][n][1]) + (v[bj][n][2] * v[bj][n][2] + v[bj][n][3] * v[bj][n][3]); }
;                 const float rn = __builtin_amdgcn_rsqf(red4(ss, fq * 16 + fr) * (1.f / 64.f) + EPS);
; #pragma unroll
;                 for (int bj = 0; bj < 2; ++bj)
; #pragma unroll
;                     for (int n = 0; n < 2; ++n) v[bj][n] = v[bj][n] * rn * g4[bj][n];
;                 if (lat) { const unsigned t = (rbase + ai * 128 + m * 16) & (SEQ - 1);
; #pragma unroll
;                     for (int bj = 0; bj < 2; ++bj) { const unsigned pos = bj ? (t & 63u) : (t >> 6); const f32x4 cs = *(const LAS f32x4*)(ropel + pos * 16u + 4u * fq), sn = *(const LAS f32x4*)(ropel + 1024u + pos * 16u + 4u * fq);
;                         const f32x4 x1 = v[bj][0], x2 = v[bj][1]; v[bj][0] = x1 * cs - x2 * sn; v[bj][1] = x2 * cs + x1 * sn; } }
;                 const unsigned ro = offA + (unsigned)(ai * 8 + m) * 32u * pitch;
;                 u32x4 w[2];
; #pragma unroll
;                 for (int bj = 0; bj < 2; ++bj) { w[bj].x = cvtpk_h(v[bj][0][0], v[bj][0][1]); w[bj].y = cvtpk_h(v[bj][0][2], v[bj][0][3]); w[bj].z = cvtpk_h(v[bj][1][0], v[bj][1][1]); w[bj].w = cvtpk_h(v[bj][1][2], v[bj][1][3]); }
;                 stg_line_pair(wst, ro, 2u * pitch, w[0], w[1], odd);
;                 asm volatile("" ::: "memory"); }
.LBB0_577:
	v_and_b32_e32 v186, 1, v202
	v_lshlrev_b32_e32 v206, 6, v186
	v_add3_u32 v206, v206, v203, v187
	v_add_u32_e32 v187, 16, v202
	v_and_b32_e32 v210, 63, v187
	v_cvt_pk_f16_f32 v152, v152, v153
	v_cvt_pk_f16_f32 v149, v148, v149
	v_mov_b32_e32 v148, v1
	v_mov_b32_e32 v187, v1
	v_cmp_eq_u32_e64 s[2:3], 0, v186
	v_mov_b32_dpp v148, v149 quad_perm:[1,0,3,2] row_mask:0xf bank_mask:0xf
	v_mov_b32_dpp v187, v152 quad_perm:[1,0,3,2] row_mask:0xf bank_mask:0xf
	v_cvt_pk_f16_f32 v153, v154, v155
	v_cvt_pk_f16_f32 v150, v150, v151
	v_cndmask_b32_e64 v148, v148, v152, s[2:3]
	v_cndmask_b32_e64 v152, v149, v187, s[2:3]
	v_mov_b32_e32 v149, v1
	v_mov_b32_e32 v187, v1
	v_cvt_pk_f16_f32 v154, v190, v191
	v_mov_b32_dpp v149, v150 quad_perm:[1,0,3,2] row_mask:0xf bank_mask:0xf
	v_mov_b32_dpp v187, v153 quad_perm:[1,0,3,2] row_mask:0xf bank_mask:0xf
	v_cvt_pk_f16_f32 v151, v194, v195
	v_cndmask_b32_e64 v149, v149, v153, s[2:3]
	v_cndmask_b32_e64 v153, v150, v187, s[2:3]
	v_mov_b32_e32 v150, v1
	v_mov_b32_e32 v187, v1
	v_cvt_pk_f16_f32 v186, v192, v193
	v_mov_b32_dpp v150, v151 quad_perm:[1,0,3,2] row_mask:0xf bank_mask:0xf
	v_mov_b32_dpp v187, v154 quad_perm:[1,0,3,2] row_mask:0xf bank_mask:0xf
	v_cndmask_b32_e64 v150, v150, v154, s[2:3]
	v_cndmask_b32_e64 v154, v151, v187, s[2:3]
	v_mov_b32_e32 v151, v1
	v_cvt_pk_f16_f32 v155, v188, v189
	v_mov_b32_e32 v187, v1
	v_mov_b32_dpp v151, v186 quad_perm:[1,0,3,2] row_mask:0xf bank_mask:0xf
	v_cndmask_b32_e64 v151, v151, v155, s[2:3]
	v_mov_b32_dpp v187, v155 quad_perm:[1,0,3,2] row_mask:0xf bank_mask:0xf
	v_cndmask_b32_e64 v155, v186, v187, s[2:3]
	global_store_dwordx4 v206, v[148:151], s[36:37] sc1
	s_and_b64 vcc, exec, s[4:5]
	v_lshlrev_b32_e32 v213, 6, v210
	v_add_u32_e32 v148, s9, v206
	global_store_dwordx4 v148, v[152:155], s[36:37] sc1
	v_mov_b32_e32 v148, v177
	v_pk_fma_f32 v[150:151], v[52:53], v[148:149], v[138:139] op_sel_hi:[1,0,1]
	v_pk_fma_f32 v[152:153], v[50:51], v[148:149], v[136:137] op_sel_hi:[1,0,1]
	v_mul_f32_e32 v154, v151, v151
	v_mul_f32_e32 v149, v153, v153
	v_fmac_f32_e32 v149, v152, v152
	v_fmac_f32_e32 v154, v150, v150
	v_add_f32_e32 v149, v149, v154
	v_pk_fma_f32 v[186:187], v[48:49], v[148:149], v[134:135] op_sel_hi:[1,0,1]
	v_pk_fma_f32 v[188:189], v[46:47], v[148:149], v[132:133] op_sel_hi:[1,0,1]
	v_mul_f32_e32 v155, v187, v187
	v_mul_f32_e32 v154, v189, v189
	v_fmac_f32_e32 v154, v188, v188
	v_fmac_f32_e32 v155, v186, v186
	v_add_f32_e32 v154, v154, v155
	v_add_f32_e32 v149, v149, v154
	v_pk_fma_f32 v[190:191], v[120:121], v[148:149], v[142:143] op_sel_hi:[1,0,1]
	v_pk_fma_f32 v[192:193], v[118:119], v[148:149], v[140:141] op_sel_hi:[1,0,1]
	v_mul_f32_e32 v155, v191, v191
	v_mul_f32_e32 v154, v193, v193
	v_fmac_f32_e32 v154, v192, v192
	v_fmac_f32_e32 v155, v190, v190
	v_add_f32_e32 v154, v154, v155
	v_add_f32_e32 v149, v149, v154
	v_pk_fma_f32 v[194:195], v[116:117], v[148:149], v[146:147] op_sel_hi:[1,0,1]
	v_pk_fma_f32 v[216:217], v[114:115], v[148:149], v[144:145] op_sel_hi:[1,0,1]
	v_mul_f32_e32 v154, v195, v195
	v_mul_f32_e32 v148, v217, v217
	v_fmac_f32_e32 v148, v216, v216
	v_fmac_f32_e32 v154, v194, v194
	v_add_f32_e32 v148, v148, v154
	v_add_f32_e32 v148, v149, v148
	v_mov_b32_e32 v149, v148
	s_nop 1
	v_permlane16_swap_b32_e32 v148, v149
	v_add_f32_e32 v148, v148, v149
	v_mov_b32_e32 v149, v148
	s_nop 1
	v_permlane32_swap_b32_e32 v148, v149
	v_add_f32_e32 v148, v148, v149
	v_fmamk_f32 v148, v148, 0x3c800000, v229
	v_rsq_f32_e32 v218, v148
	s_nop 0
	v_pk_mul_f32 v[148:149], v[152:153], v[218:219] op_sel_hi:[1,0]
	v_pk_mul_f32 v[150:151], v[150:151], v[218:219] op_sel_hi:[1,0]
	v_pk_mul_f32 v[152:153], v[184:185], v[148:149]
	v_pk_mul_f32 v[154:155], v[182:183], v[150:151]
	v_pk_mul_f32 v[148:149], v[188:189], v[218:219] op_sel_hi:[1,0]
	v_pk_mul_f32 v[150:151], v[186:187], v[218:219] op_sel_hi:[1,0]
	v_pk_mul_f32 v[188:189], v[180:181], v[148:149]
	v_pk_mul_f32 v[186:187], v[178:179], v[150:151]
	v_pk_mul_f32 v[148:149], v[192:193], v[218:219] op_sel_hi:[1,0]
	v_pk_mul_f32 v[150:151], v[190:191], v[218:219] op_sel_hi:[1,0]
	v_pk_mul_f32 v[192:193], v[216:217], v[218:219] op_sel_hi:[1,0]
	v_pk_mul_f32 v[190:191], v[194:195], v[218:219] op_sel_hi:[1,0]
	v_pk_mul_f32 v[150:151], v[160:161], v[150:151]
	v_pk_mul_f32 v[148:149], v[162:163], v[148:149]
	v_pk_mul_f32 v[190:191], v[156:157], v[190:191]
	v_pk_mul_f32 v[192:193], v[158:159], v[192:193]
	s_cbranch_vccnz .LBB0_579
	v_add_u32_e32 v194, 16, v201
	v_and_b32_e32 v194, 0x7c0, v194
	v_add_u32_e32 v195, v205, v194
	v_add_u32_e32 v194, v204, v194
	ds_read_b128 v[216:219], v195
	ds_read_b128 v[220:223], v194
	s_waitcnt lgkmcnt(0)
	v_pk_mul_f32 v[224:225], v[188:189], v[220:221]
	v_pk_mul_f32 v[194:195], v[186:187], v[222:223]
	v_pk_fma_f32 v[224:225], v[152:153], v[216:217], v[224:225] neg_lo:[0,0,1] neg_hi:[0,0,1]
	v_pk_mul_f32 v[152:153], v[152:153], v[220:221]
	v_pk_fma_f32 v[226:227], v[154:155], v[218:219], v[194:195] neg_lo:[0,0,1] neg_hi:[0,0,1]
	v_pk_mul_f32 v[154:155], v[154:155], v[222:223]
	v_pk_fma_f32 v[188:189], v[188:189], v[216:217], v[152:153]
	v_add_u32_e32 v152, v205, v213
	v_add_u32_e32 v194, v204, v213
	v_pk_fma_f32 v[186:187], v[186:187], v[218:219], v[154:155]
	ds_read_b128 v[152:155], v152
	ds_read_b128 v[216:219], v194
	s_waitcnt lgkmcnt(0)
	v_pk_mul_f32 v[194:195], v[190:191], v[218:219]
	v_pk_mul_f32 v[220:221], v[192:193], v[216:217]
	v_pk_fma_f32 v[222:223], v[150:151], v[154:155], v[194:195] neg_lo:[0,0,1] neg_hi:[0,0,1]
	v_pk_fma_f32 v[220:221], v[148:149], v[152:153], v[220:221] neg_lo:[0,0,1] neg_hi:[0,0,1]
	v_pk_mul_f32 v[150:151], v[150:151], v[218:219]
	v_pk_mul_f32 v[148:149], v[148:149], v[216:217]
	v_pk_fma_f32 v[190:191], v[190:191], v[154:155], v[150:151]
	v_pk_fma_f32 v[192:193], v[192:193], v[152:153], v[148:149]
	v_mov_b64_e32 v[148:149], v[220:221]
	v_mov_b64_e32 v[152:153], v[224:225]
	v_mov_b64_e32 v[150:151], v[222:223]
	v_mov_b64_e32 v[154:155], v[226:227]
; #define LAS __attribute__((address_space(3)))
; __device__ __forceinline__ unsigned cvtpk_h(float lo, float hi) { f32x2 v = {lo, hi}; h16x2 b = __builtin_convertvector(v, h16x2); return __builtin_bit_cast(unsigned, b); }
;     __device__ __forceinline__ void operator()(const f32x4 (&acc)[2][2][4][2], const pg8::Unit& u, int wr, int wc, int fr, int fq) const {
;     ...
;             for (int m = 0; m < 4; ++m) { const float r = rs[ai][m]; f32x4 v[2][2]; float ss = 0.f;
; #pragma unroll
;                 for (int bj = 0; bj < 2; ++bj)
; #pragma unroll
;                     for (int n = 0; n < 2; ++n) { v[bj][n] = acc[ai][bj][m][n] * r + bv[bj][n]; ss += (v[bj][n][0] * v[bj][n][0] + v[bj][n][1] * v[bj][n][1]) + (v[bj][n][2] * v[bj][n][2] + v[bj][n][3] * v[bj][n][3]); }
;                 const float rn = __builtin_amdgcn_rsqf(red4(ss, fq * 16 + fr) * (1.f / 64.f) + EPS);
; #pragma unroll
;                 for (int bj = 0; bj < 2; ++bj)
; #pragma unroll
;                     for (int n = 0; n < 2; ++n) v[bj][n] = v[bj][n] * rn * g4[bj][n];
;                 if (lat) { const unsigned t = (rbase + ai * 128 + m * 16) & (SEQ - 1);
; #pragma unroll
;                     for (int bj = 0; bj < 2; ++bj) { const unsigned pos = bj ? (t & 63u) : (t >> 6); const f32x4 cs = *(const LAS f32x4*)(ropel + pos * 16u + 4u * fq), sn = *(const LAS f32x4*)(ropel + 1024u + pos * 16u + 4u * fq);
;                         const f32x4 x1 = v[bj][0], x2 = v[bj][1]; v[bj][0] = x1 * cs - x2 * sn; v[bj][1] = x2 * cs + x1 * sn; } }
;                 const unsigned ro = offA + (unsigned)(ai * 8 + m) * 32u * pitch;
;                 u32x4 w[2];
; #pragma unroll
;                 for (int bj = 0; bj < 2; ++bj) { w[bj].x = cvtpk_h(v[bj][0][0], v[bj][0][1]); w[bj].y = cvtpk_h(v[bj][0][2], v[bj][0][3]); w[bj].z = cvtpk_h(v[bj][1][0], v[bj][1][1]); w[bj].w = cvtpk_h(v[bj][1][2], v[bj][1][3]); }
;                 stg_line_pair(wst, ro, 2u * pitch, w[0], w[1], odd);
.LBB0_579:
	v_cvt_pk_f16_f32 v152, v152, v153
	v_cvt_pk_f16_f32 v153, v154, v155
	v_cvt_pk_f16_f32 v154, v188, v189
	v_cvt_pk_f16_f32 v149, v148, v149
	v_mov_b32_e32 v148, v1
	v_mov_b32_e32 v188, v1
	v_cvt_pk_f16_f32 v150, v150, v151
	v_mov_b32_dpp v148, v149 quad_perm:[1,0,3,2] row_mask:0xf bank_mask:0xf
	v_mov_b32_dpp v188, v152 quad_perm:[1,0,3,2] row_mask:0xf bank_mask:0xf
	v_cndmask_b32_e64 v148, v148, v152, s[2:3]
	v_cndmask_b32_e64 v152, v149, v188, s[2:3]
	v_mov_b32_e32 v149, v1
	v_mov_b32_e32 v188, v1
	v_cvt_pk_f16_f32 v151, v192, v193
	v_mov_b32_dpp v149, v150 quad_perm:[1,0,3,2] row_mask:0xf bank_mask:0xf
	v_mov_b32_dpp v188, v153 quad_perm:[1,0,3,2] row_mask:0xf bank_mask:0xf
	v_cndmask_b32_e64 v149, v149, v153, s[2:3]
	v_cndmask_b32_e64 v153, v150, v188, s[2:3]
	v_mov_b32_e32 v150, v1
	v_mov_b32_e32 v188, v1
	v_cvt_pk_f16_f32 v155, v186, v187
	v_mov_b32_dpp v150, v151 quad_perm:[1,0,3,2] row_mask:0xf bank_mask:0xf
	v_mov_b32_dpp v188, v154 quad_perm:[1,0,3,2] row_mask:0xf bank_mask:0xf
	v_cvt_pk_f16_f32 v186, v190, v191
	v_cndmask_b32_e64 v150, v150, v154, s[2:3]
	v_cndmask_b32_e64 v154, v151, v188, s[2:3]
	v_mov_b32_e32 v151, v1
	v_mov_b32_e32 v188, v1
	v_lshl_add_u32 v187, 32, s42, v206
	v_mov_b32_dpp v151, v186 quad_perm:[1,0,3,2] row_mask:0xf bank_mask:0xf
	v_mov_b32_dpp v188, v155 quad_perm:[1,0,3,2] row_mask:0xf bank_mask:0xf
	v_cndmask_b32_e64 v151, v151, v155, s[2:3]
	v_cndmask_b32_e64 v155, v186, v188, s[2:3]
	global_store_dwordx4 v187, v[148:151], s[36:37] sc1
	v_pk_fma_f32 v[188:189], v[42:43], v[174:175], v[132:133] op_sel_hi:[1,0,1]
	v_pk_fma_f32 v[190:191], v[112:113], v[174:175], v[142:143] op_sel_hi:[1,0,1]
	v_add_u32_e32 v148, s9, v187
	global_store_dwordx4 v148, v[152:155], s[36:37] sc1
	v_pk_fma_f32 v[148:149], v[56:57], v[174:175], v[138:139] op_sel_hi:[1,0,1]
	v_pk_fma_f32 v[150:151], v[54:55], v[174:175], v[136:137] op_sel_hi:[1,0,1]
	v_mul_f32_e32 v153, v149, v149
	v_mul_f32_e32 v152, v151, v151
	v_fmac_f32_e32 v152, v150, v150
	v_fmac_f32_e32 v153, v148, v148
	v_pk_fma_f32 v[186:187], v[44:45], v[174:175], v[134:135] op_sel_hi:[1,0,1]
	v_add_f32_e32 v152, v152, v153
	v_mul_f32_e32 v153, v189, v189
	v_mul_f32_e32 v154, v187, v187
	v_fmac_f32_e32 v153, v188, v188
	v_fmac_f32_e32 v154, v186, v186
	v_add_f32_e32 v153, v153, v154
	v_pk_fma_f32 v[192:193], v[110:111], v[174:175], v[140:141] op_sel_hi:[1,0,1]
	v_add_f32_e32 v152, v152, v153
	v_mul_f32_e32 v153, v193, v193
	v_mul_f32_e32 v154, v191, v191
	v_fmac_f32_e32 v153, v192, v192
	v_fmac_f32_e32 v154, v190, v190
	v_xor_b32_e32 v210, 32, v214
	v_add_f32_e32 v153, v153, v154
	v_pk_fma_f32 v[194:195], v[108:109], v[174:175], v[146:147] op_sel_hi:[1,0,1]
	v_pk_fma_f32 v[214:215], v[106:107], v[174:175], v[144:145] op_sel_hi:[1,0,1]
	v_add_f32_e32 v152, v152, v153
	v_mul_f32_e32 v153, v215, v215
	v_mul_f32_e32 v154, v195, v195
	v_fmac_f32_e32 v153, v214, v214
	v_fmac_f32_e32 v154, v194, v194
	v_add_f32_e32 v153, v153, v154
	v_add_f32_e32 v152, v152, v153
	v_mov_b32_e32 v153, v152
	s_nop 1
	v_permlane16_swap_b32_e32 v152, v153
	v_add_f32_e32 v152, v152, v153
	v_mov_b32_e32 v153, v152
	s_nop 1
	v_permlane32_swap_b32_e32 v152, v153
	v_add_f32_e32 v152, v152, v153
	v_fmamk_f32 v152, v152, 0x3c800000, v229
	v_rsq_f32_e32 v216, v152
	s_and_b64 vcc, exec, s[4:5]
	v_pk_mul_f32 v[150:151], v[150:151], v[216:217] op_sel_hi:[1,0]
	v_pk_mul_f32 v[148:149], v[148:149], v[216:217] op_sel_hi:[1,0]
	v_pk_mul_f32 v[152:153], v[184:185], v[150:151]
	v_pk_mul_f32 v[154:155], v[182:183], v[148:149]
	v_pk_mul_f32 v[148:149], v[188:189], v[216:217] op_sel_hi:[1,0]
	v_pk_mul_f32 v[150:151], v[186:187], v[216:217] op_sel_hi:[1,0]
	v_pk_mul_f32 v[188:189], v[180:181], v[148:149]
	v_pk_mul_f32 v[186:187], v[178:179], v[150:151]
	v_pk_mul_f32 v[148:149], v[192:193], v[216:217] op_sel_hi:[1,0]
	v_pk_mul_f32 v[150:151], v[190:191], v[216:217] op_sel_hi:[1,0]
	v_pk_mul_f32 v[192:193], v[214:215], v[216:217] op_sel_hi:[1,0]
	v_pk_mul_f32 v[190:191], v[194:195], v[216:217] op_sel_hi:[1,0]
	v_pk_mul_f32 v[150:151], v[160:161], v[150:151]
	v_pk_mul_f32 v[148:149], v[162:163], v[148:149]
	v_pk_mul_f32 v[190:191], v[156:157], v[190:191]
	v_pk_mul_f32 v[192:193], v[158:159], v[192:193]
	v_lshlrev_b32_e32 v195, 6, v210
	s_cbranch_vccnz .LBB0_581
	v_add_u32_e32 v194, 32, v201
	v_and_b32_e32 v194, 0x7c0, v194
	v_add_u32_e32 v210, v205, v194
	v_add_u32_e32 v194, v204, v194
	ds_read_b128 v[214:217], v210
	ds_read_b128 v[218:221], v194
	v_add_u32_e32 v194, v204, v195
	s_waitcnt lgkmcnt(0)
	v_pk_mul_f32 v[222:223], v[186:187], v[220:221]
	v_pk_mul_f32 v[226:227], v[188:189], v[218:219]
	v_pk_fma_f32 v[224:225], v[154:155], v[216:217], v[222:223] neg_lo:[0,0,1] neg_hi:[0,0,1]
	v_pk_fma_f32 v[222:223], v[152:153], v[214:215], v[226:227] neg_lo:[0,0,1] neg_hi:[0,0,1]
	v_pk_mul_f32 v[152:153], v[152:153], v[218:219]
	v_pk_mul_f32 v[154:155], v[154:155], v[220:221]
	v_pk_fma_f32 v[188:189], v[188:189], v[214:215], v[152:153]
	v_add_u32_e32 v152, v205, v195
	v_pk_fma_f32 v[186:187], v[186:187], v[216:217], v[154:155]
	ds_read_b128 v[152:155], v152
	ds_read_b128 v[214:217], v194
	s_waitcnt lgkmcnt(0)
	v_pk_mul_f32 v[218:219], v[190:191], v[216:217]
	v_pk_mul_f32 v[226:227], v[192:193], v[214:215]
	v_pk_fma_f32 v[220:221], v[150:151], v[154:155], v[218:219] neg_lo:[0,0,1] neg_hi:[0,0,1]
	v_pk_fma_f32 v[218:219], v[148:149], v[152:153], v[226:227] neg_lo:[0,0,1] neg_hi:[0,0,1]
	v_pk_mul_f32 v[150:151], v[150:151], v[216:217]
	v_pk_mul_f32 v[148:149], v[148:149], v[214:215]
	v_pk_fma_f32 v[190:191], v[190:191], v[154:155], v[150:151]
	v_pk_fma_f32 v[192:193], v[192:193], v[152:153], v[148:149]
	v_mov_b64_e32 v[148:149], v[218:219]
	v_mov_b64_e32 v[152:153], v[222:223]
	v_mov_b64_e32 v[150:151], v[220:221]
	v_mov_b64_e32 v[154:155], v[224:225]
; #define LAS __attribute__((address_space(3)))
; __device__ __forceinline__ unsigned cvtpk_h(float lo, float hi) { f32x2 v = {lo, hi}; h16x2 b = __builtin_convertvector(v, h16x2); return __builtin_bit_cast(unsigned, b); }
;     __device__ __forceinline__ void operator()(const f32x4 (&acc)[2][2][4][2], const pg8::Unit& u, int wr, int wc, int fr, int fq) const {
;     ...
;             for (int m = 0; m < 4; ++m) { const float r = rs[ai][m]; f32x4 v[2][2]; float ss = 0.f;
; #pragma unroll
;                 for (int bj = 0; bj < 2; ++bj)
; #pragma unroll
;                     for (int n = 0; n < 2; ++n) { v[bj][n] = acc[ai][bj][m][n] * r + bv[bj][n]; ss += (v[bj][n][0] * v[bj][n][0] + v[bj][n][1] * v[bj][n][1]) + (v[bj][n][2] * v[bj][n][2] + v[bj][n][3] * v[bj][n][3]); }
;                 const float rn = __builtin_amdgcn_rsqf(red4(ss, fq * 16 + fr) * (1.f / 64.f) + EPS);
; #pragma unroll
;                 for (int bj = 0; bj < 2; ++bj)
; #pragma unroll
;                     for (int n = 0; n < 2; ++n) v[bj][n] = v[bj][n] * rn * g4[bj][n];
;                 if (lat) { const unsigned t = (rbase + ai * 128 + m * 16) & (SEQ - 1);
; #pragma unroll
;                     for (int bj = 0; bj < 2; ++bj) { const unsigned pos = bj ? (t & 63u) : (t >> 6); const f32x4 cs = *(const LAS f32x4*)(ropel + pos * 16u + 4u * fq), sn = *(const LAS f32x4*)(ropel + 1024u + pos * 16u + 4u * fq);
;                         const f32x4 x1 = v[bj][0], x2 = v[bj][1]; v[bj][0] = x1 * cs - x2 * sn; v[bj][1] = x2 * cs + x1 * sn; } }
;                 const unsigned ro = offA + (unsigned)(ai * 8 + m) * 32u * pitch;
;                 u32x4 w[2];
; #pragma unroll
;                 for (int bj = 0; bj < 2; ++bj) { w[bj].x = cvtpk_h(v[bj][0][0], v[bj][0][1]); w[bj].y = cvtpk_h(v[bj][0][2], v[bj][0][3]); w[bj].z = cvtpk_h(v[bj][1][0], v[bj][1][1]); w[bj].w = cvtpk_h(v[bj][1][2], v[bj][1][3]); }
;                 stg_line_pair(wst, ro, 2u * pitch, w[0], w[1], odd);
.LBB0_581:
	v_cvt_pk_f16_f32 v152, v152, v153
	v_cvt_pk_f16_f32 v153, v154, v155
	v_cvt_pk_f16_f32 v154, v188, v189
	v_cvt_pk_f16_f32 v149, v148, v149
	v_mov_b32_e32 v148, v1
	v_mov_b32_e32 v188, v1
	v_cvt_pk_f16_f32 v150, v150, v151
	v_mov_b32_dpp v148, v149 quad_perm:[1,0,3,2] row_mask:0xf bank_mask:0xf
	v_mov_b32_dpp v188, v152 quad_perm:[1,0,3,2] row_mask:0xf bank_mask:0xf
	v_cndmask_b32_e64 v148, v148, v152, s[2:3]
	v_cndmask_b32_e64 v152, v149, v188, s[2:3]
	v_mov_b32_e32 v149, v1
	v_mov_b32_e32 v188, v1
	v_cvt_pk_f16_f32 v151, v192, v193
	v_mov_b32_dpp v149, v150 quad_perm:[1,0,3,2] row_mask:0xf bank_mask:0xf
	v_mov_b32_dpp v188, v153 quad_perm:[1,0,3,2] row_mask:0xf bank_mask:0xf
	v_cndmask_b32_e64 v149, v149, v153, s[2:3]
	v_cndmask_b32_e64 v153, v150, v188, s[2:3]
	v_mov_b32_e32 v150, v1
	v_mov_b32_e32 v188, v1
	v_cvt_pk_f16_f32 v155, v186, v187
	v_mov_b32_dpp v150, v151 quad_perm:[1,0,3,2] row_mask:0xf bank_mask:0xf
	v_mov_b32_dpp v188, v154 quad_perm:[1,0,3,2] row_mask:0xf bank_mask:0xf
	v_cvt_pk_f16_f32 v186, v190, v191
	v_cndmask_b32_e64 v150, v150, v154, s[2:3]
	v_cndmask_b32_e64 v154, v151, v188, s[2:3]
	v_mov_b32_e32 v151, v1
	v_mov_b32_e32 v188, v1
	v_lshl_add_u32 v187, 64, s42, v206
	v_mov_b32_dpp v151, v186 quad_perm:[1,0,3,2] row_mask:0xf bank_mask:0xf
	v_mov_b32_dpp v188, v155 quad_perm:[1,0,3,2] row_mask:0xf bank_mask:0xf
	v_cndmask_b32_e64 v151, v151, v155, s[2:3]
	v_cndmask_b32_e64 v155, v186, v188, s[2:3]
	global_store_dwordx4 v187, v[148:151], s[36:37] sc1
	v_add_u32_e32 v194, 48, v202
	v_and_b32_e32 v210, 63, v194
	v_add_u32_e32 v148, s9, v187
	global_store_dwordx4 v148, v[152:155], s[36:37] sc1
	v_mov_b32_e32 v148, v175
	v_pk_fma_f32 v[150:151], v[40:41], v[148:149], v[138:139] op_sel_hi:[1,0,1]
	v_pk_fma_f32 v[152:153], v[38:39], v[148:149], v[136:137] op_sel_hi:[1,0,1]
	v_mul_f32_e32 v154, v151, v151
	v_mul_f32_e32 v149, v153, v153
	v_fmac_f32_e32 v149, v152, v152
	v_fmac_f32_e32 v154, v150, v150
	v_add_f32_e32 v149, v149, v154
	v_pk_fma_f32 v[186:187], v[36:37], v[148:149], v[134:135] op_sel_hi:[1,0,1]
	v_pk_fma_f32 v[188:189], v[34:35], v[148:149], v[132:133] op_sel_hi:[1,0,1]
	v_mul_f32_e32 v155, v187, v187
	v_mul_f32_e32 v154, v189, v189
	v_fmac_f32_e32 v154, v188, v188
	v_fmac_f32_e32 v155, v186, v186
	v_add_f32_e32 v154, v154, v155
	v_add_f32_e32 v149, v149, v154
	v_pk_fma_f32 v[190:191], v[104:105], v[148:149], v[142:143] op_sel_hi:[1,0,1]
	v_pk_fma_f32 v[192:193], v[102:103], v[148:149], v[140:141] op_sel_hi:[1,0,1]
	v_mul_f32_e32 v155, v191, v191
	v_mul_f32_e32 v154, v193, v193
	v_fmac_f32_e32 v154, v192, v192
	v_fmac_f32_e32 v155, v190, v190
	v_add_f32_e32 v154, v154, v155
	v_add_f32_e32 v149, v149, v154
	v_pk_fma_f32 v[214:215], v[100:101], v[148:149], v[146:147] op_sel_hi:[1,0,1]
	v_pk_fma_f32 v[216:217], v[98:99], v[148:149], v[144:145] op_sel_hi:[1,0,1]
	v_mul_f32_e32 v154, v215, v215
	v_mul_f32_e32 v148, v217, v217
	v_fmac_f32_e32 v148, v216, v216
	v_fmac_f32_e32 v154, v214, v214
	v_add_f32_e32 v148, v148, v154
	v_add_f32_e32 v148, v149, v148
	v_mov_b32_e32 v149, v148
	s_nop 1
	v_permlane16_swap_b32_e32 v148, v149
	v_add_f32_e32 v148, v148, v149
	v_mov_b32_e32 v149, v148
	s_nop 1
	v_permlane32_swap_b32_e32 v148, v149
	v_add_f32_e32 v148, v148, v149
	v_fmamk_f32 v148, v148, 0x3c800000, v229
	v_rsq_f32_e32 v194, v148
	s_and_b64 vcc, exec, s[4:5]
	v_pk_mul_f32 v[148:149], v[152:153], v[194:195] op_sel_hi:[1,0]
	v_pk_mul_f32 v[150:151], v[150:151], v[194:195] op_sel_hi:[1,0]
	v_pk_mul_f32 v[152:153], v[184:185], v[148:149]
	v_pk_mul_f32 v[154:155], v[182:183], v[150:151]
	v_pk_mul_f32 v[148:149], v[188:189], v[194:195] op_sel_hi:[1,0]
	v_pk_mul_f32 v[150:151], v[186:187], v[194:195] op_sel_hi:[1,0]
	v_pk_mul_f32 v[188:189], v[180:181], v[148:149]
	v_pk_mul_f32 v[186:187], v[178:179], v[150:151]
	v_pk_mul_f32 v[148:149], v[192:193], v[194:195] op_sel_hi:[1,0]
	v_pk_mul_f32 v[150:151], v[190:191], v[194:195] op_sel_hi:[1,0]
	v_pk_mul_f32 v[192:193], v[216:217], v[194:195] op_sel_hi:[1,0]
	v_pk_mul_f32 v[190:191], v[214:215], v[194:195] op_sel_hi:[1,0]
	v_pk_mul_f32 v[150:151], v[160:161], v[150:151]
	v_pk_mul_f32 v[148:149], v[162:163], v[148:149]
	v_pk_mul_f32 v[190:191], v[156:157], v[190:191]
	v_pk_mul_f32 v[192:193], v[158:159], v[192:193]
	v_lshlrev_b32_e32 v194, 6, v210
	s_cbranch_vccnz .LBB0_583
	v_add_u32_e32 v210, 48, v201
	v_and_b32_e32 v210, 0x7c0, v210
	v_add_u32_e32 v211, v205, v210
	v_add_u32_e32 v210, v204, v210
	ds_read_b128 v[214:217], v211
	ds_read_b128 v[218:221], v210
	v_add_u32_e32 v210, v204, v194
	s_waitcnt lgkmcnt(0)
	v_pk_mul_f32 v[222:223], v[186:187], v[220:221]
	v_pk_mul_f32 v[226:227], v[188:189], v[218:219]
	v_pk_fma_f32 v[224:225], v[154:155], v[216:217], v[222:223] neg_lo:[0,0,1] neg_hi:[0,0,1]
	v_pk_fma_f32 v[222:223], v[152:153], v[214:215], v[226:227] neg_lo:[0,0,1] neg_hi:[0,0,1]
	v_pk_mul_f32 v[152:153], v[152:153], v[218:219]
	v_pk_mul_f32 v[154:155], v[154:155], v[220:221]
	v_pk_fma_f32 v[188:189], v[188:189], v[214:215], v[152:153]
	v_add_u32_e32 v152, v205, v194
	v_pk_fma_f32 v[186:187], v[186:187], v[216:217], v[154:155]
	ds_read_b128 v[152:155], v152
	ds_read_b128 v[214:217], v210
	s_waitcnt lgkmcnt(0)
	v_pk_mul_f32 v[218:219], v[190:191], v[216:217]
	v_pk_mul_f32 v[226:227], v[192:193], v[214:215]
	v_pk_fma_f32 v[220:221], v[150:151], v[154:155], v[218:219] neg_lo:[0,0,1] neg_hi:[0,0,1]
	v_pk_fma_f32 v[218:219], v[148:149], v[152:153], v[226:227] neg_lo:[0,0,1] neg_hi:[0,0,1]
	v_pk_mul_f32 v[150:151], v[150:151], v[216:217]
	v_pk_mul_f32 v[148:149], v[148:149], v[214:215]
	v_pk_fma_f32 v[190:191], v[190:191], v[154:155], v[150:151]
	v_pk_fma_f32 v[192:193], v[192:193], v[152:153], v[148:149]
	v_mov_b64_e32 v[148:149], v[218:219]
	v_mov_b64_e32 v[152:153], v[222:223]
	v_mov_b64_e32 v[150:151], v[220:221]
	v_mov_b64_e32 v[154:155], v[224:225]
; #define LAS __attribute__((address_space(3)))
; __device__ __forceinline__ unsigned cvtpk_h(float lo, float hi) { f32x2 v = {lo, hi}; h16x2 b = __builtin_convertvector(v, h16x2); return __builtin_bit_cast(unsigned, b); }
;     __device__ __forceinline__ void operator()(const f32x4 (&acc)[2][2][4][2], const pg8::Unit& u, int wr, int wc, int fr, int fq) const {
;     ...
;             for (int m = 0; m < 4; ++m) { const float r = rs[ai][m]; f32x4 v[2][2]; float ss = 0.f;
; #pragma unroll
;                 for (int bj = 0; bj < 2; ++bj)
; #pragma unroll
;                     for (int n = 0; n < 2; ++n) { v[bj][n] = acc[ai][bj][m][n] * r + bv[bj][n]; ss += (v[bj][n][0] * v[bj][n][0] + v[bj][n][1] * v[bj][n][1]) + (v[bj][n][2] * v[bj][n][2] + v[bj][n][3] * v[bj][n][3]); }
;                 const float rn = __builtin_amdgcn_rsqf(red4(ss, fq * 16 + fr) * (1.f / 64.f) + EPS);
; #pragma unroll
;                 for (int bj = 0; bj < 2; ++bj)
; #pragma unroll
;                     for (int n = 0; n < 2; ++n) v[bj][n] = v[bj][n] * rn * g4[bj][n];
;                 if (lat) { const unsigned t = (rbase + ai * 128 + m * 16) & (SEQ - 1);
; #pragma unroll
;                     for (int bj = 0; bj < 2; ++bj) { const unsigned pos = bj ? (t & 63u) : (t >> 6); const f32x4 cs = *(const LAS f32x4*)(ropel + pos * 16u + 4u * fq), sn = *(const LAS f32x4*)(ropel + 1024u + pos * 16u + 4u * fq);
;                         const f32x4 x1 = v[bj][0], x2 = v[bj][1]; v[bj][0] = x1 * cs - x2 * sn; v[bj][1] = x2 * cs + x1 * sn; } }
;                 const unsigned ro = offA + (unsigned)(ai * 8 + m) * 32u * pitch;
;                 u32x4 w[2];
; #pragma unroll
;                 for (int bj = 0; bj < 2; ++bj) { w[bj].x = cvtpk_h(v[bj][0][0], v[bj][0][1]); w[bj].y = cvtpk_h(v[bj][0][2], v[bj][0][3]); w[bj].z = cvtpk_h(v[bj][1][0], v[bj][1][1]); w[bj].w = cvtpk_h(v[bj][1][2], v[bj][1][3]); }
;                 stg_line_pair(wst, ro, 2u * pitch, w[0], w[1], odd);
.LBB0_583:
	v_cvt_pk_f16_f32 v152, v152, v153
	v_cvt_pk_f16_f32 v153, v154, v155
	v_cvt_pk_f16_f32 v154, v188, v189
	v_cvt_pk_f16_f32 v149, v148, v149
	v_mov_b32_e32 v148, v1
	v_mov_b32_e32 v188, v1
	v_cvt_pk_f16_f32 v150, v150, v151
	v_mov_b32_dpp v148, v149 quad_perm:[1,0,3,2] row_mask:0xf bank_mask:0xf
	v_mov_b32_dpp v188, v152 quad_perm:[1,0,3,2] row_mask:0xf bank_mask:0xf
	v_cndmask_b32_e64 v148, v148, v152, s[2:3]
	v_cndmask_b32_e64 v152, v149, v188, s[2:3]
	v_mov_b32_e32 v149, v1
	v_mov_b32_e32 v188, v1
	v_cvt_pk_f16_f32 v151, v192, v193
	v_mov_b32_dpp v149, v150 quad_perm:[1,0,3,2] row_mask:0xf bank_mask:0xf
	v_mov_b32_dpp v188, v153 quad_perm:[1,0,3,2] row_mask:0xf bank_mask:0xf
	v_cndmask_b32_e64 v149, v149, v153, s[2:3]
	v_cndmask_b32_e64 v153, v150, v188, s[2:3]
	v_mov_b32_e32 v150, v1
	v_mov_b32_e32 v188, v1
	v_cvt_pk_f16_f32 v155, v186, v187
	v_mov_b32_dpp v150, v151 quad_perm:[1,0,3,2] row_mask:0xf bank_mask:0xf
	v_mov_b32_dpp v188, v154 quad_perm:[1,0,3,2] row_mask:0xf bank_mask:0xf
	v_cvt_pk_f16_f32 v186, v190, v191
	v_cndmask_b32_e64 v150, v150, v154, s[2:3]
	v_cndmask_b32_e64 v154, v151, v188, s[2:3]
	v_mov_b32_e32 v151, v1
	s_lshl_b32 s38, 0x60, s42
	v_mov_b32_e32 v188, v1
	v_mov_b32_dpp v151, v186 quad_perm:[1,0,3,2] row_mask:0xf bank_mask:0xf
	v_add_u32_e32 v187, s38, v206
	v_mov_b32_dpp v188, v155 quad_perm:[1,0,3,2] row_mask:0xf bank_mask:0xf
	v_cndmask_b32_e64 v151, v151, v155, s[2:3]
	v_cndmask_b32_e64 v155, v186, v188, s[2:3]
	global_store_dwordx4 v187, v[148:151], s[36:37] sc1
	v_pk_fma_f32 v[188:189], v[26:27], v[172:173], v[132:133] op_sel_hi:[1,0,1]
	v_pk_fma_f32 v[190:191], v[96:97], v[172:173], v[142:143] op_sel_hi:[1,0,1]
	v_add_u32_e32 v148, s9, v187
	global_store_dwordx4 v148, v[152:155], s[36:37] sc1
	v_pk_fma_f32 v[148:149], v[32:33], v[172:173], v[138:139] op_sel_hi:[1,0,1]
	v_pk_fma_f32 v[150:151], v[30:31], v[172:173], v[136:137] op_sel_hi:[1,0,1]
	v_mul_f32_e32 v153, v149, v149
	v_mul_f32_e32 v152, v151, v151
	v_fmac_f32_e32 v152, v150, v150
	v_fmac_f32_e32 v153, v148, v148
	v_pk_fma_f32 v[186:187], v[28:29], v[172:173], v[134:135] op_sel_hi:[1,0,1]
	v_add_f32_e32 v152, v152, v153
	v_mul_f32_e32 v153, v189, v189
	v_mul_f32_e32 v154, v187, v187
	v_fmac_f32_e32 v153, v188, v188
	v_fmac_f32_e32 v154, v186, v186
	v_add_f32_e32 v153, v153, v154
	v_pk_fma_f32 v[192:193], v[94:95], v[172:173], v[140:141] op_sel_hi:[1,0,1]
	v_add_f32_e32 v152, v152, v153
	v_mul_f32_e32 v153, v193, v193
	v_mul_f32_e32 v154, v191, v191
	v_fmac_f32_e32 v153, v192, v192
	v_fmac_f32_e32 v154, v190, v190
	v_add_f32_e32 v153, v153, v154
	v_pk_fma_f32 v[214:215], v[92:93], v[172:173], v[146:147] op_sel_hi:[1,0,1]
	v_pk_fma_f32 v[216:217], v[90:91], v[172:173], v[144:145] op_sel_hi:[1,0,1]
	v_add_f32_e32 v152, v153, v152
	v_mul_f32_e32 v153, v217, v217
	v_mul_f32_e32 v154, v215, v215
	v_fmac_f32_e32 v153, v216, v216
	v_fmac_f32_e32 v154, v214, v214
	v_add_f32_e32 v153, v153, v154
	v_add_f32_e32 v152, v153, v152
	v_mov_b32_e32 v153, v152
	s_nop 1
	v_permlane16_swap_b32_e32 v152, v153
	v_add_f32_e32 v152, v152, v153
	v_mov_b32_e32 v153, v152
	s_nop 1
	v_permlane32_swap_b32_e32 v152, v153
	v_add_f32_e32 v152, v152, v153
	v_fmamk_f32 v152, v152, 0x3c800000, v229
	v_rsq_f32_e32 v218, v152
	s_and_b64 vcc, exec, s[4:5]
	v_pk_mul_f32 v[150:151], v[150:151], v[218:219] op_sel_hi:[1,0]
	v_pk_mul_f32 v[148:149], v[148:149], v[218:219] op_sel_hi:[1,0]
	v_pk_mul_f32 v[152:153], v[184:185], v[150:151]
	v_pk_mul_f32 v[154:155], v[182:183], v[148:149]
	v_pk_mul_f32 v[148:149], v[188:189], v[218:219] op_sel_hi:[1,0]
	v_pk_mul_f32 v[150:151], v[186:187], v[218:219] op_sel_hi:[1,0]
	v_pk_mul_f32 v[188:189], v[180:181], v[148:149]
	v_pk_mul_f32 v[186:187], v[178:179], v[150:151]
	v_pk_mul_f32 v[148:149], v[192:193], v[218:219] op_sel_hi:[1,0]
	v_pk_mul_f32 v[150:151], v[190:191], v[218:219] op_sel_hi:[1,0]
	v_pk_mul_f32 v[192:193], v[216:217], v[218:219] op_sel_hi:[1,0]
	v_pk_mul_f32 v[190:191], v[214:215], v[218:219] op_sel_hi:[1,0]
	v_pk_mul_f32 v[150:151], v[160:161], v[150:151]
	v_pk_mul_f32 v[148:149], v[162:163], v[148:149]
	v_pk_mul_f32 v[190:191], v[156:157], v[190:191]
	v_pk_mul_f32 v[192:193], v[158:159], v[192:193]
	s_cbranch_vccnz .LBB0_585
	v_add_u32_e32 v210, 0x80, v201
	v_and_b32_e32 v210, 0x7c0, v210
	v_add_u32_e32 v211, v205, v210
	v_add_u32_e32 v210, v204, v210
	ds_read_b128 v[214:217], v211
	ds_read_b128 v[218:221], v210
	s_waitcnt lgkmcnt(0)
	v_pk_mul_f32 v[222:223], v[186:187], v[220:221]
	v_pk_mul_f32 v[226:227], v[188:189], v[218:219]
	v_pk_fma_f32 v[224:225], v[154:155], v[216:217], v[222:223] neg_lo:[0,0,1] neg_hi:[0,0,1]
	v_pk_fma_f32 v[222:223], v[152:153], v[214:215], v[226:227] neg_lo:[0,0,1] neg_hi:[0,0,1]
	v_pk_mul_f32 v[152:153], v[152:153], v[218:219]
	v_pk_mul_f32 v[154:155], v[154:155], v[220:221]
	v_pk_fma_f32 v[188:189], v[188:189], v[214:215], v[152:153]
	v_add_u32_e32 v152, v205, v207
	v_add_u32_e32 v207, v204, v207
	v_pk_fma_f32 v[186:187], v[186:187], v[216:217], v[154:155]
	ds_read_b128 v[152:155], v152
	ds_read_b128 v[214:217], v207
	s_waitcnt lgkmcnt(0)
	v_pk_mul_f32 v[218:219], v[190:191], v[216:217]
	v_pk_mul_f32 v[226:227], v[192:193], v[214:215]
	v_pk_fma_f32 v[220:221], v[150:151], v[154:155], v[218:219] neg_lo:[0,0,1] neg_hi:[0,0,1]
	v_pk_fma_f32 v[218:219], v[148:149], v[152:153], v[226:227] neg_lo:[0,0,1] neg_hi:[0,0,1]
	v_pk_mul_f32 v[150:151], v[150:151], v[216:217]
	v_pk_mul_f32 v[148:149], v[148:149], v[214:215]
	v_pk_fma_f32 v[190:191], v[190:191], v[154:155], v[150:151]
	v_pk_fma_f32 v[192:193], v[192:193], v[152:153], v[148:149]
	v_mov_b64_e32 v[148:149], v[218:219]
	v_mov_b64_e32 v[152:153], v[222:223]
	v_mov_b64_e32 v[150:151], v[220:221]
	v_mov_b64_e32 v[154:155], v[224:225]
; #define LAS __attribute__((address_space(3)))
; __device__ __forceinline__ unsigned cvtpk_h(float lo, float hi) { f32x2 v = {lo, hi}; h16x2 b = __builtin_convertvector(v, h16x2); return __builtin_bit_cast(unsigned, b); }
;     __device__ __forceinline__ void operator()(const f32x4 (&acc)[2][2][4][2], const pg8::Unit& u, int wr, int wc, int fr, int fq) const {
;     ...
;             for (int m = 0; m < 4; ++m) { const float r = rs[ai][m]; f32x4 v[2][2]; float ss = 0.f;
; #pragma unroll
;                 for (int bj = 0; bj < 2; ++bj)
; #pragma unroll
;                     for (int n = 0; n < 2; ++n) { v[bj][n] = acc[ai][bj][m][n] * r + bv[bj][n]; ss += (v[bj][n][0] * v[bj][n][0] + v[bj][n][1] * v[bj][n][1]) + (v[bj][n][2] * v[bj][n][2] + v[bj][n][3] * v[bj][n][3]); }
;                 const float rn = __builtin_amdgcn_rsqf(red4(ss, fq * 16 + fr) * (1.f / 64.f) + EPS);
; #pragma unroll
;                 for (int bj = 0; bj < 2; ++bj)
; #pragma unroll
;                     for (int n = 0; n < 2; ++n) v[bj][n] = v[bj][n] * rn * g4[bj][n];
;                 if (lat) { const unsigned t = (rbase + ai * 128 + m * 16) & (SEQ - 1);
; #pragma unroll
;                     for (int bj = 0; bj < 2; ++bj) { const unsigned pos = bj ? (t & 63u) : (t >> 6); const f32x4 cs = *(const LAS f32x4*)(ropel + pos * 16u + 4u * fq), sn = *(const LAS f32x4*)(ropel + 1024u + pos * 16u + 4u * fq);
;                         const f32x4 x1 = v[bj][0], x2 = v[bj][1]; v[bj][0] = x1 * cs - x2 * sn; v[bj][1] = x2 * cs + x1 * sn; } }
;                 const unsigned ro = offA + (unsigned)(ai * 8 + m) * 32u * pitch;
;                 u32x4 w[2];
; #pragma unroll
;                 for (int bj = 0; bj < 2; ++bj) { w[bj].x = cvtpk_h(v[bj][0][0], v[bj][0][1]); w[bj].y = cvtpk_h(v[bj][0][2], v[bj][0][3]); w[bj].z = cvtpk_h(v[bj][1][0], v[bj][1][1]); w[bj].w = cvtpk_h(v[bj][1][2], v[bj][1][3]); }
;                 stg_line_pair(wst, ro, 2u * pitch, w[0], w[1], odd);
.LBB0_585:
	v_cvt_pk_f16_f32 v152, v152, v153
	v_cvt_pk_f16_f32 v153, v154, v155
	v_cvt_pk_f16_f32 v154, v188, v189
	v_cvt_pk_f16_f32 v149, v148, v149
	v_mov_b32_e32 v148, v1
	v_mov_b32_e32 v188, v1
	v_cvt_pk_f16_f32 v150, v150, v151
	v_mov_b32_dpp v148, v149 quad_perm:[1,0,3,2] row_mask:0xf bank_mask:0xf
	v_mov_b32_dpp v188, v152 quad_perm:[1,0,3,2] row_mask:0xf bank_mask:0xf
	v_cndmask_b32_e64 v148, v148, v152, s[2:3]
	v_cndmask_b32_e64 v152, v149, v188, s[2:3]
	v_mov_b32_e32 v149, v1
	v_mov_b32_e32 v188, v1
	v_cvt_pk_f16_f32 v151, v192, v193
	v_mov_b32_dpp v149, v150 quad_perm:[1,0,3,2] row_mask:0xf bank_mask:0xf
	v_mov_b32_dpp v188, v153 quad_perm:[1,0,3,2] row_mask:0xf bank_mask:0xf
	v_cndmask_b32_e64 v149, v149, v153, s[2:3]
	v_cndmask_b32_e64 v153, v150, v188, s[2:3]
	v_mov_b32_e32 v150, v1
	v_mov_b32_e32 v188, v1
	v_cvt_pk_f16_f32 v155, v186, v187
	v_mov_b32_dpp v150, v151 quad_perm:[1,0,3,2] row_mask:0xf bank_mask:0xf
	v_mov_b32_dpp v188, v154 quad_perm:[1,0,3,2] row_mask:0xf bank_mask:0xf
	v_cvt_pk_f16_f32 v186, v190, v191
	v_cndmask_b32_e64 v150, v150, v154, s[2:3]
	v_cndmask_b32_e64 v154, v151, v188, s[2:3]
	v_mov_b32_e32 v151, v1
	s_lshl_b32 s38, 0x100, s42
	v_mov_b32_e32 v188, v1
	v_mov_b32_dpp v151, v186 quad_perm:[1,0,3,2] row_mask:0xf bank_mask:0xf
	v_add_u32_e32 v187, s38, v206
	v_mov_b32_dpp v188, v155 quad_perm:[1,0,3,2] row_mask:0xf bank_mask:0xf
	v_cndmask_b32_e64 v151, v151, v155, s[2:3]
	v_cndmask_b32_e64 v155, v186, v188, s[2:3]
	global_store_dwordx4 v187, v[148:151], s[36:37] sc1
	s_and_b64 vcc, exec, s[4:5]
	s_nop 0
	v_add_u32_e32 v148, s9, v187
	global_store_dwordx4 v148, v[152:155], s[36:37] sc1
	v_mov_b32_e32 v148, v173
	v_pk_fma_f32 v[150:151], v[24:25], v[148:149], v[138:139] op_sel_hi:[1,0,1]
	v_pk_fma_f32 v[152:153], v[22:23], v[148:149], v[136:137] op_sel_hi:[1,0,1]
	v_mul_f32_e32 v154, v151, v151
	v_mul_f32_e32 v149, v153, v153
	v_fmac_f32_e32 v149, v152, v152
	v_fmac_f32_e32 v154, v150, v150
	v_add_f32_e32 v149, v149, v154
	v_pk_fma_f32 v[186:187], v[20:21], v[148:149], v[134:135] op_sel_hi:[1,0,1]
	v_pk_fma_f32 v[188:189], v[18:19], v[148:149], v[132:133] op_sel_hi:[1,0,1]
	v_mul_f32_e32 v155, v187, v187
	v_mul_f32_e32 v154, v189, v189
	v_fmac_f32_e32 v154, v188, v188
	v_fmac_f32_e32 v155, v186, v186
	v_add_f32_e32 v154, v154, v155
	v_add_f32_e32 v149, v149, v154
	v_pk_fma_f32 v[190:191], v[88:89], v[148:149], v[142:143] op_sel_hi:[1,0,1]
	v_pk_fma_f32 v[192:193], v[86:87], v[148:149], v[140:141] op_sel_hi:[1,0,1]
	v_mul_f32_e32 v155, v191, v191
	v_mul_f32_e32 v154, v193, v193
	v_fmac_f32_e32 v154, v192, v192
	v_fmac_f32_e32 v155, v190, v190
	v_add_f32_e32 v154, v154, v155
	v_add_f32_e32 v149, v154, v149
	v_pk_fma_f32 v[214:215], v[84:85], v[148:149], v[146:147] op_sel_hi:[1,0,1]
	v_pk_fma_f32 v[216:217], v[82:83], v[148:149], v[144:145] op_sel_hi:[1,0,1]
	v_mul_f32_e32 v154, v215, v215
	v_mul_f32_e32 v148, v217, v217
	v_fmac_f32_e32 v148, v216, v216
	v_fmac_f32_e32 v154, v214, v214
	v_add_f32_e32 v148, v148, v154
	v_add_f32_e32 v148, v148, v149
	v_mov_b32_e32 v149, v148
	s_nop 1
	v_permlane16_swap_b32_e32 v148, v149
	v_add_f32_e32 v148, v148, v149
	v_mov_b32_e32 v149, v148
	s_nop 1
	v_permlane32_swap_b32_e32 v148, v149
	v_add_f32_e32 v148, v148, v149
	v_fmamk_f32 v148, v148, 0x3c800000, v229
	v_rsq_f32_e32 v218, v148
	s_nop 0
	v_pk_mul_f32 v[148:149], v[152:153], v[218:219] op_sel_hi:[1,0]
	v_pk_mul_f32 v[150:151], v[150:151], v[218:219] op_sel_hi:[1,0]
	v_pk_mul_f32 v[152:153], v[184:185], v[148:149]
	v_pk_mul_f32 v[154:155], v[182:183], v[150:151]
	v_pk_mul_f32 v[148:149], v[188:189], v[218:219] op_sel_hi:[1,0]
	v_pk_mul_f32 v[150:151], v[186:187], v[218:219] op_sel_hi:[1,0]
	v_pk_mul_f32 v[188:189], v[180:181], v[148:149]
	v_pk_mul_f32 v[186:187], v[178:179], v[150:151]
	v_pk_mul_f32 v[148:149], v[192:193], v[218:219] op_sel_hi:[1,0]
	v_pk_mul_f32 v[150:151], v[190:191], v[218:219] op_sel_hi:[1,0]
	v_pk_mul_f32 v[192:193], v[216:217], v[218:219] op_sel_hi:[1,0]
	v_pk_mul_f32 v[190:191], v[214:215], v[218:219] op_sel_hi:[1,0]
	v_pk_mul_f32 v[150:151], v[160:161], v[150:151]
	v_pk_mul_f32 v[148:149], v[162:163], v[148:149]
	v_pk_mul_f32 v[190:191], v[156:157], v[190:191]
	v_pk_mul_f32 v[192:193], v[158:159], v[192:193]
	s_cbranch_vccnz .LBB0_587
	v_add_u32_e32 v207, 0x90, v201
	v_and_b32_e32 v207, 0x7c0, v207
	v_add_u32_e32 v210, v205, v207
	v_add_u32_e32 v207, v204, v207
	ds_read_b128 v[214:217], v210
	ds_read_b128 v[218:221], v207
	v_add_u32_e32 v207, v204, v213
	s_waitcnt lgkmcnt(0)
	v_pk_mul_f32 v[222:223], v[186:187], v[220:221]
	v_pk_mul_f32 v[226:227], v[188:189], v[218:219]
	v_pk_fma_f32 v[224:225], v[154:155], v[216:217], v[222:223] neg_lo:[0,0,1] neg_hi:[0,0,1]
	v_pk_fma_f32 v[222:223], v[152:153], v[214:215], v[226:227] neg_lo:[0,0,1] neg_hi:[0,0,1]
	v_pk_mul_f32 v[152:153], v[152:153], v[218:219]
	v_pk_mul_f32 v[154:155], v[154:155], v[220:221]
	v_pk_fma_f32 v[188:189], v[188:189], v[214:215], v[152:153]
	v_add_u32_e32 v152, v205, v213
	v_pk_fma_f32 v[186:187], v[186:187], v[216:217], v[154:155]
	ds_read_b128 v[152:155], v152
	ds_read_b128 v[214:217], v207
	s_waitcnt lgkmcnt(0)
	v_pk_mul_f32 v[218:219], v[190:191], v[216:217]
	v_pk_mul_f32 v[226:227], v[192:193], v[214:215]
	v_pk_fma_f32 v[220:221], v[150:151], v[154:155], v[218:219] neg_lo:[0,0,1] neg_hi:[0,0,1]
	v_pk_fma_f32 v[218:219], v[148:149], v[152:153], v[226:227] neg_lo:[0,0,1] neg_hi:[0,0,1]
	v_pk_mul_f32 v[150:151], v[150:151], v[216:217]
	v_pk_mul_f32 v[148:149], v[148:149], v[214:215]
	v_pk_fma_f32 v[190:191], v[190:191], v[154:155], v[150:151]
	v_pk_fma_f32 v[192:193], v[192:193], v[152:153], v[148:149]
	v_mov_b64_e32 v[148:149], v[218:219]
	v_mov_b64_e32 v[152:153], v[222:223]
	v_mov_b64_e32 v[150:151], v[220:221]
	v_mov_b64_e32 v[154:155], v[224:225]
; #define LAS __attribute__((address_space(3)))
; __device__ __forceinline__ void stg_line_pair(void* base, unsigned roA, unsigned rowb, const u32x4 w0, const u32x4 w1, bool odd) {
;     u32x4 a, b;
; #pragma unroll
;     for (int c = 0; c < 4; ++c) { const unsigned p1 = (unsigned)__builtin_amdgcn_update_dpp(0, (int)w1[c], 0xB1, 0xF, 0xF, false), p0 = (unsigned)__builtin_amdgcn_update_dpp(0, (int)w0[c], 0xB1, 0xF, 0xF, false);
;         a[c] = odd ? p1 : w0[c]; b[c] = odd ? w1[c] : p0; }
;     stg_u4(base, roA, a); stg_u4(base, roA + rowb, b);
; }
;     __device__ __forceinline__ void operator()(const f32x4 (&acc)[2][2][4][2], const pg8::Unit& u, int wr, int wc, int fr, int fq) const {
;     ...
;             for (int m = 0; m < 4; ++m) { const float r = rs[ai][m]; f32x4 v[2][2]; float ss = 0.f;
; #pragma unroll
;                 for (int bj = 0; bj < 2; ++bj)
; #pragma unroll
;                     for (int n = 0; n < 2; ++n) { v[bj][n] = acc[ai][bj][m][n] * r + bv[bj][n]; ss += (v[bj][n][0] * v[bj][n][0] + v[bj][n][1] * v[bj][n][1]) + (v[bj][n][2] * v[bj][n][2] + v[bj][n][3] * v[bj][n][3]); }
;                 const float rn = __builtin_amdgcn_rsqf(red4(ss, fq * 16 + fr) * (1.f / 64.f) + EPS);
; #pragma unroll
;                 for (int bj = 0; bj < 2; ++bj)
; #pragma unroll
;                     for (int n = 0; n < 2; ++n) v[bj][n] = v[bj][n] * rn * g4[bj][n];
;                 if (lat) { const unsigned t = (rbase + ai * 128 + m * 16) & (SEQ - 1);
; #pragma unroll
;                     for (int bj = 0; bj < 2; ++bj) { const unsigned pos = bj ? (t & 63u) : (t >> 6); const f32x4 cs = *(const LAS f32x4*)(ropel + pos * 16u + 4u * fq), sn = *(const LAS f32x4*)(ropel + 1024u + pos * 16u + 4u * fq);
;                         const f32x4 x1 = v[bj][0], x2 = v[bj][1]; v[bj][0] = x1 * cs - x2 * sn; v[bj][1] = x2 * cs + x1 * sn; } }
;                 const unsigned ro = offA + (unsigned)(ai * 8 + m) * 32u * pitch;
;                 u32x4 w[2];
; #pragma unroll
;                 for (int bj = 0; bj < 2; ++bj) { w[bj].x = cvtpk_h(v[bj][0][0], v[bj][0][1]); w[bj].y = cvtpk_h(v[bj][0][2], v[bj][0][3]); w[bj].z = cvtpk_h(v[bj][1][0], v[bj][1][1]); w[bj].w = cvtpk_h(v[bj][1][2], v[bj][1][3]); }
;                 stg_line_pair(wst, ro, 2u * pitch, w[0], w[1], odd);
;                 asm volatile("" ::: "memory"); }
.LBB0_587:
	v_cvt_pk_f16_f32 v152, v152, v153
	v_cvt_pk_f16_f32 v153, v154, v155
	v_cvt_pk_f16_f32 v154, v188, v189
	v_cvt_pk_f16_f32 v149, v148, v149
	v_mov_b32_e32 v148, v1
	v_mov_b32_e32 v188, v1
	v_cvt_pk_f16_f32 v150, v150, v151
	v_mov_b32_dpp v148, v149 quad_perm:[1,0,3,2] row_mask:0xf bank_mask:0xf
	v_mov_b32_dpp v188, v152 quad_perm:[1,0,3,2] row_mask:0xf bank_mask:0xf
	v_cndmask_b32_e64 v148, v148, v152, s[2:3]
	v_cndmask_b32_e64 v152, v149, v188, s[2:3]
	v_mov_b32_e32 v149, v1
	v_mov_b32_e32 v188, v1
	v_cvt_pk_f16_f32 v151, v192, v193
	v_mov_b32_dpp v149, v150 quad_perm:[1,0,3,2] row_mask:0xf bank_mask:0xf
	v_mov_b32_dpp v188, v153 quad_perm:[1,0,3,2] row_mask:0xf bank_mask:0xf
	v_cndmask_b32_e64 v149, v149, v153, s[2:3]
	v_cndmask_b32_e64 v153, v150, v188, s[2:3]
	v_mov_b32_e32 v150, v1
	v_mov_b32_e32 v188, v1
	v_cvt_pk_f16_f32 v155, v186, v187
	v_mov_b32_dpp v150, v151 quad_perm:[1,0,3,2] row_mask:0xf bank_mask:0xf
	v_mov_b32_dpp v188, v154 quad_perm:[1,0,3,2] row_mask:0xf bank_mask:0xf
	v_cvt_pk_f16_f32 v186, v190, v191
	v_cndmask_b32_e64 v150, v150, v154, s[2:3]
	v_cndmask_b32_e64 v154, v151, v188, s[2:3]
	v_mov_b32_e32 v151, v1
	s_lshl_b32 s38, 0x120, s42
	v_mov_b32_e32 v188, v1
	v_mov_b32_dpp v151, v186 quad_perm:[1,0,3,2] row_mask:0xf bank_mask:0xf
	v_add_u32_e32 v187, s38, v206
	v_mov_b32_dpp v188, v155 quad_perm:[1,0,3,2] row_mask:0xf bank_mask:0xf
	v_cndmask_b32_e64 v151, v151, v155, s[2:3]
	v_cndmask_b32_e64 v155, v186, v188, s[2:3]
	global_store_dwordx4 v187, v[148:151], s[36:37] sc1
	v_pk_fma_f32 v[188:189], v[10:11], v[170:171], v[132:133] op_sel_hi:[1,0,1]
	v_pk_fma_f32 v[190:191], v[80:81], v[170:171], v[142:143] op_sel_hi:[1,0,1]
	v_add_u32_e32 v148, s9, v187
	global_store_dwordx4 v148, v[152:155], s[36:37] sc1
	v_pk_fma_f32 v[148:149], v[16:17], v[170:171], v[138:139] op_sel_hi:[1,0,1]
	v_pk_fma_f32 v[150:151], v[14:15], v[170:171], v[136:137] op_sel_hi:[1,0,1]
	v_mul_f32_e32 v153, v149, v149
	v_mul_f32_e32 v152, v151, v151
	v_fmac_f32_e32 v152, v150, v150
	v_fmac_f32_e32 v153, v148, v148
	v_pk_fma_f32 v[186:187], v[12:13], v[170:171], v[134:135] op_sel_hi:[1,0,1]
	v_add_f32_e32 v152, v152, v153
	v_mul_f32_e32 v153, v189, v189
	v_mul_f32_e32 v154, v187, v187
	v_fmac_f32_e32 v153, v188, v188
	v_fmac_f32_e32 v154, v186, v186
	v_add_f32_e32 v153, v153, v154
	v_pk_fma_f32 v[192:193], v[78:79], v[170:171], v[140:141] op_sel_hi:[1,0,1]
	v_add_f32_e32 v152, v152, v153
	v_mul_f32_e32 v153, v193, v193
	v_mul_f32_e32 v154, v191, v191
	v_fmac_f32_e32 v153, v192, v192
	v_fmac_f32_e32 v154, v190, v190
	v_add_f32_e32 v153, v153, v154
	v_pk_fma_f32 v[214:215], v[76:77], v[170:171], v[146:147] op_sel_hi:[1,0,1]
	v_pk_fma_f32 v[216:217], v[74:75], v[170:171], v[144:145] op_sel_hi:[1,0,1]
	v_add_f32_e32 v152, v153, v152
	v_mul_f32_e32 v153, v217, v217
	v_mul_f32_e32 v154, v215, v215
	v_fmac_f32_e32 v153, v216, v216
	v_fmac_f32_e32 v154, v214, v214
	v_add_f32_e32 v153, v153, v154
	v_add_f32_e32 v152, v153, v152
	v_mov_b32_e32 v153, v152
	s_nop 1
	v_permlane16_swap_b32_e32 v152, v153
	v_add_f32_e32 v152, v152, v153
	v_mov_b32_e32 v153, v152
	s_nop 1
	v_permlane32_swap_b32_e32 v152, v153
	v_add_f32_e32 v152, v152, v153
	v_fmamk_f32 v152, v152, 0x3c800000, v229
	v_rsq_f32_e32 v218, v152
	s_and_b64 vcc, exec, s[4:5]
	v_pk_mul_f32 v[150:151], v[150:151], v[218:219] op_sel_hi:[1,0]
	v_pk_mul_f32 v[148:149], v[148:149], v[218:219] op_sel_hi:[1,0]
	v_pk_mul_f32 v[152:153], v[184:185], v[150:151]
	v_pk_mul_f32 v[154:155], v[182:183], v[148:149]
	v_pk_mul_f32 v[148:149], v[188:189], v[218:219] op_sel_hi:[1,0]
	v_pk_mul_f32 v[150:151], v[186:187], v[218:219] op_sel_hi:[1,0]
	v_pk_mul_f32 v[188:189], v[180:181], v[148:149]
	v_pk_mul_f32 v[186:187], v[178:179], v[150:151]
	v_pk_mul_f32 v[148:149], v[192:193], v[218:219] op_sel_hi:[1,0]
	v_pk_mul_f32 v[150:151], v[190:191], v[218:219] op_sel_hi:[1,0]
	v_pk_mul_f32 v[192:193], v[216:217], v[218:219] op_sel_hi:[1,0]
	v_pk_mul_f32 v[190:191], v[214:215], v[218:219] op_sel_hi:[1,0]
	v_pk_mul_f32 v[150:151], v[160:161], v[150:151]
	v_pk_mul_f32 v[148:149], v[162:163], v[148:149]
	v_pk_mul_f32 v[190:191], v[156:157], v[190:191]
	v_pk_mul_f32 v[192:193], v[158:159], v[192:193]
	s_cbranch_vccnz .LBB0_589
	v_add_u32_e32 v207, 0xa0, v201
	v_and_b32_e32 v207, 0x7c0, v207
	v_add_u32_e32 v210, v205, v207
	v_add_u32_e32 v207, v204, v207
	ds_read_b128 v[214:217], v210
	ds_read_b128 v[218:221], v207
	s_waitcnt lgkmcnt(0)
	v_pk_mul_f32 v[222:223], v[186:187], v[220:221]
	v_pk_mul_f32 v[226:227], v[188:189], v[218:219]
	v_pk_fma_f32 v[224:225], v[154:155], v[216:217], v[222:223] neg_lo:[0,0,1] neg_hi:[0,0,1]
	v_pk_fma_f32 v[222:223], v[152:153], v[214:215], v[226:227] neg_lo:[0,0,1] neg_hi:[0,0,1]
	v_pk_mul_f32 v[152:153], v[152:153], v[218:219]
	v_pk_mul_f32 v[154:155], v[154:155], v[220:221]
	v_pk_fma_f32 v[188:189], v[188:189], v[214:215], v[152:153]
	v_add_u32_e32 v152, v205, v195
	v_add_u32_e32 v195, v204, v195
	v_pk_fma_f32 v[186:187], v[186:187], v[216:217], v[154:155]
	ds_read_b128 v[152:155], v152
	ds_read_b128 v[214:217], v195
	s_waitcnt lgkmcnt(0)
	v_pk_mul_f32 v[218:219], v[190:191], v[216:217]
	v_pk_mul_f32 v[226:227], v[192:193], v[214:215]
	v_pk_fma_f32 v[220:221], v[150:151], v[154:155], v[218:219] neg_lo:[0,0,1] neg_hi:[0,0,1]
	v_pk_fma_f32 v[218:219], v[148:149], v[152:153], v[226:227] neg_lo:[0,0,1] neg_hi:[0,0,1]
	v_pk_mul_f32 v[150:151], v[150:151], v[216:217]
	v_pk_mul_f32 v[148:149], v[148:149], v[214:215]
	v_pk_fma_f32 v[190:191], v[190:191], v[154:155], v[150:151]
	v_pk_fma_f32 v[192:193], v[192:193], v[152:153], v[148:149]
	v_mov_b64_e32 v[148:149], v[218:219]
	v_mov_b64_e32 v[152:153], v[222:223]
	v_mov_b64_e32 v[150:151], v[220:221]
	v_mov_b64_e32 v[154:155], v[224:225]
; #define LAS __attribute__((address_space(3)))
; __device__ __forceinline__ void stg_line_pair(void* base, unsigned roA, unsigned rowb, const u32x4 w0, const u32x4 w1, bool odd) {
;     u32x4 a, b;
; #pragma unroll
;     for (int c = 0; c < 4; ++c) { const unsigned p1 = (unsigned)__builtin_amdgcn_update_dpp(0, (int)w1[c], 0xB1, 0xF, 0xF, false), p0 = (unsigned)__builtin_amdgcn_update_dpp(0, (int)w0[c], 0xB1, 0xF, 0xF, false);
;         a[c] = odd ? p1 : w0[c]; b[c] = odd ? w1[c] : p0; }
;     stg_u4(base, roA, a); stg_u4(base, roA + rowb, b);
; }
;     __device__ __forceinline__ void operator()(const f32x4 (&acc)[2][2][4][2], const pg8::Unit& u, int wr, int wc, int fr, int fq) const {
;     ...
;             for (int m = 0; m < 4; ++m) { const float r = rs[ai][m]; f32x4 v[2][2]; float ss = 0.f;
; #pragma unroll
;                 for (int bj = 0; bj < 2; ++bj)
; #pragma unroll
;                     for (int n = 0; n < 2; ++n) { v[bj][n] = acc[ai][bj][m][n] * r + bv[bj][n]; ss += (v[bj][n][0] * v[bj][n][0] + v[bj][n][1] * v[bj][n][1]) + (v[bj][n][2] * v[bj][n][2] + v[bj][n][3] * v[bj][n][3]); }
;                 const float rn = __builtin_amdgcn_rsqf(red4(ss, fq * 16 + fr) * (1.f / 64.f) + EPS);
; #pragma unroll
;                 for (int bj = 0; bj < 2; ++bj)
; #pragma unroll
;                     for (int n = 0; n < 2; ++n) v[bj][n] = v[bj][n] * rn * g4[bj][n];
;                 if (lat) { const unsigned t = (rbase + ai * 128 + m * 16) & (SEQ - 1);
; #pragma unroll
;                     for (int bj = 0; bj < 2; ++bj) { const unsigned pos = bj ? (t & 63u) : (t >> 6); const f32x4 cs = *(const LAS f32x4*)(ropel + pos * 16u + 4u * fq), sn = *(const LAS f32x4*)(ropel + 1024u + pos * 16u + 4u * fq);
;                         const f32x4 x1 = v[bj][0], x2 = v[bj][1]; v[bj][0] = x1 * cs - x2 * sn; v[bj][1] = x2 * cs + x1 * sn; } }
;                 const unsigned ro = offA + (unsigned)(ai * 8 + m) * 32u * pitch;
;                 u32x4 w[2];
; #pragma unroll
;                 for (int bj = 0; bj < 2; ++bj) { w[bj].x = cvtpk_h(v[bj][0][0], v[bj][0][1]); w[bj].y = cvtpk_h(v[bj][0][2], v[bj][0][3]); w[bj].z = cvtpk_h(v[bj][1][0], v[bj][1][1]); w[bj].w = cvtpk_h(v[bj][1][2], v[bj][1][3]); }
;                 stg_line_pair(wst, ro, 2u * pitch, w[0], w[1], odd);
;                 asm volatile("" ::: "memory"); }
.LBB0_589:
	v_cvt_pk_f16_f32 v152, v152, v153
	v_cvt_pk_f16_f32 v153, v154, v155
	v_cvt_pk_f16_f32 v154, v188, v189
	v_cvt_pk_f16_f32 v149, v148, v149
	v_mov_b32_e32 v148, v1
	v_mov_b32_e32 v188, v1
	v_cvt_pk_f16_f32 v150, v150, v151
	v_mov_b32_dpp v148, v149 quad_perm:[1,0,3,2] row_mask:0xf bank_mask:0xf
	v_mov_b32_dpp v188, v152 quad_perm:[1,0,3,2] row_mask:0xf bank_mask:0xf
	v_cndmask_b32_e64 v148, v148, v152, s[2:3]
	v_cndmask_b32_e64 v152, v149, v188, s[2:3]
	v_mov_b32_e32 v149, v1
	v_mov_b32_e32 v188, v1
	v_cvt_pk_f16_f32 v151, v192, v193
	v_mov_b32_dpp v149, v150 quad_perm:[1,0,3,2] row_mask:0xf bank_mask:0xf
	v_mov_b32_dpp v188, v153 quad_perm:[1,0,3,2] row_mask:0xf bank_mask:0xf
	v_cndmask_b32_e64 v149, v149, v153, s[2:3]
	v_cndmask_b32_e64 v153, v150, v188, s[2:3]
	v_mov_b32_e32 v150, v1
	v_mov_b32_e32 v188, v1
	v_cvt_pk_f16_f32 v155, v186, v187
	v_mov_b32_dpp v150, v151 quad_perm:[1,0,3,2] row_mask:0xf bank_mask:0xf
	v_mov_b32_dpp v188, v154 quad_perm:[1,0,3,2] row_mask:0xf bank_mask:0xf
	v_cvt_pk_f16_f32 v186, v190, v191
	v_cndmask_b32_e64 v150, v150, v154, s[2:3]
	v_cndmask_b32_e64 v154, v151, v188, s[2:3]
	v_mov_b32_e32 v151, v1
	s_lshl_b32 s38, 0x140, s42
	v_mov_b32_e32 v188, v1
	v_mov_b32_dpp v151, v186 quad_perm:[1,0,3,2] row_mask:0xf bank_mask:0xf
	v_add_u32_e32 v187, s38, v206
	v_mov_b32_dpp v188, v155 quad_perm:[1,0,3,2] row_mask:0xf bank_mask:0xf
	v_cndmask_b32_e64 v151, v151, v155, s[2:3]
	v_cndmask_b32_e64 v155, v186, v188, s[2:3]
	global_store_dwordx4 v187, v[148:151], s[36:37] sc1
	s_and_b64 vcc, exec, s[4:5]
	s_nop 0
	v_add_u32_e32 v148, s9, v187
	global_store_dwordx4 v148, v[152:155], s[36:37] sc1
	v_mov_b32_e32 v148, v171
	v_pk_fma_f32 v[150:151], v[8:9], v[148:149], v[138:139] op_sel_hi:[1,0,1]
	v_pk_fma_f32 v[152:153], v[6:7], v[148:149], v[136:137] op_sel_hi:[1,0,1]
	v_mul_f32_e32 v154, v151, v151
	v_mul_f32_e32 v149, v153, v153
	v_fmac_f32_e32 v149, v152, v152
	v_fmac_f32_e32 v154, v150, v150
	v_add_f32_e32 v149, v149, v154
	v_pk_fma_f32 v[186:187], v[4:5], v[148:149], v[134:135] op_sel_hi:[1,0,1]
	v_pk_fma_f32 v[188:189], v[2:3], v[148:149], v[132:133] op_sel_hi:[1,0,1]
	v_mul_f32_e32 v155, v187, v187
	v_mul_f32_e32 v154, v189, v189
	v_fmac_f32_e32 v154, v188, v188
	v_fmac_f32_e32 v155, v186, v186
	v_add_f32_e32 v154, v154, v155
	v_add_f32_e32 v149, v149, v154
	v_pk_fma_f32 v[190:191], v[64:65], v[148:149], v[142:143] op_sel_hi:[1,0,1]
	v_pk_fma_f32 v[192:193], v[62:63], v[148:149], v[140:141] op_sel_hi:[1,0,1]
	v_mul_f32_e32 v155, v191, v191
	v_mul_f32_e32 v154, v193, v193
	v_fmac_f32_e32 v154, v192, v192
	v_fmac_f32_e32 v155, v190, v190
	v_add_f32_e32 v154, v154, v155
	v_add_f32_e32 v149, v154, v149
	v_pk_fma_f32 v[214:215], v[60:61], v[148:149], v[146:147] op_sel_hi:[1,0,1]
	v_pk_fma_f32 v[216:217], v[58:59], v[148:149], v[144:145] op_sel_hi:[1,0,1]
	v_mul_f32_e32 v154, v215, v215
	v_mul_f32_e32 v148, v217, v217
	v_fmac_f32_e32 v148, v216, v216
	v_fmac_f32_e32 v154, v214, v214
	v_add_f32_e32 v148, v148, v154
	v_add_f32_e32 v148, v148, v149
	v_mov_b32_e32 v149, v148
	s_nop 1
	v_permlane16_swap_b32_e32 v148, v149
	v_add_f32_e32 v148, v148, v149
	v_mov_b32_e32 v149, v148
	s_nop 1
	v_permlane32_swap_b32_e32 v148, v149
	v_add_f32_e32 v148, v148, v149
	v_fmamk_f32 v148, v148, 0x3c800000, v229
	v_rsq_f32_e32 v218, v148
	s_nop 0
	v_pk_mul_f32 v[148:149], v[152:153], v[218:219] op_sel_hi:[1,0]
	v_pk_mul_f32 v[150:151], v[150:151], v[218:219] op_sel_hi:[1,0]
	v_pk_mul_f32 v[152:153], v[184:185], v[148:149]
	v_pk_mul_f32 v[154:155], v[182:183], v[150:151]
	v_pk_mul_f32 v[148:149], v[188:189], v[218:219] op_sel_hi:[1,0]
	v_pk_mul_f32 v[150:151], v[186:187], v[218:219] op_sel_hi:[1,0]
	v_pk_mul_f32 v[180:181], v[180:181], v[148:149]
	v_pk_mul_f32 v[178:179], v[178:179], v[150:151]
	v_pk_mul_f32 v[148:149], v[192:193], v[218:219] op_sel_hi:[1,0]
	v_pk_mul_f32 v[150:151], v[190:191], v[218:219] op_sel_hi:[1,0]
	v_pk_mul_f32 v[148:149], v[162:163], v[148:149]
	v_pk_mul_f32 v[150:151], v[160:161], v[150:151]
	v_pk_mul_f32 v[160:161], v[216:217], v[218:219] op_sel_hi:[1,0]
	v_pk_mul_f32 v[162:163], v[214:215], v[218:219] op_sel_hi:[1,0]
	v_pk_mul_f32 v[158:159], v[158:159], v[160:161]
	v_pk_mul_f32 v[156:157], v[156:157], v[162:163]
	s_cbranch_vccnz .LBB0_591
	v_add_u32_e32 v160, 0xb0, v201
	v_and_b32_e32 v182, 0x7c0, v160
	v_add_u32_e32 v160, v205, v182
	v_add_u32_e32 v182, v204, v182
	ds_read_b128 v[160:163], v160
	ds_read_b128 v[182:185], v182
	s_waitcnt lgkmcnt(0)
	v_pk_mul_f32 v[186:187], v[178:179], v[184:185]
	v_pk_mul_f32 v[190:191], v[180:181], v[182:183]
	v_pk_fma_f32 v[188:189], v[154:155], v[162:163], v[186:187] neg_lo:[0,0,1] neg_hi:[0,0,1]
	v_pk_fma_f32 v[186:187], v[152:153], v[160:161], v[190:191] neg_lo:[0,0,1] neg_hi:[0,0,1]
	v_pk_mul_f32 v[152:153], v[152:153], v[182:183]
	v_pk_mul_f32 v[154:155], v[154:155], v[184:185]
	v_pk_fma_f32 v[180:181], v[180:181], v[160:161], v[152:153]
	v_add_u32_e32 v152, v205, v194
	v_add_u32_e32 v160, v204, v194
	v_pk_fma_f32 v[178:179], v[178:179], v[162:163], v[154:155]
	ds_read_b128 v[152:155], v152
	ds_read_b128 v[160:163], v160
	s_waitcnt lgkmcnt(0)
	v_pk_mul_f32 v[182:183], v[156:157], v[162:163]
	v_pk_mul_f32 v[190:191], v[158:159], v[160:161]
	v_pk_fma_f32 v[184:185], v[150:151], v[154:155], v[182:183] neg_lo:[0,0,1] neg_hi:[0,0,1]
	v_pk_fma_f32 v[182:183], v[148:149], v[152:153], v[190:191] neg_lo:[0,0,1] neg_hi:[0,0,1]
	v_pk_mul_f32 v[150:151], v[150:151], v[162:163]
	v_pk_mul_f32 v[148:149], v[148:149], v[160:161]
	v_pk_fma_f32 v[156:157], v[156:157], v[154:155], v[150:151]
	v_pk_fma_f32 v[158:159], v[158:159], v[152:153], v[148:149]
	v_mov_b64_e32 v[148:149], v[182:183]
	v_mov_b64_e32 v[152:153], v[186:187]
	v_mov_b64_e32 v[150:151], v[184:185]
	v_mov_b64_e32 v[154:155], v[188:189]
; __device__ __forceinline__ unsigned cvtpk_h(float lo, float hi) { f32x2 v = {lo, hi}; h16x2 b = __builtin_convertvector(v, h16x2); return __builtin_bit_cast(unsigned, b); }
;     __device__ __forceinline__ void operator()(const f32x4 (&acc)[2][2][4][2], const pg8::Unit& u, int wr, int wc, int fr, int fq) const {
;     ...
;                 const unsigned ro = offA + (unsigned)(ai * 8 + m) * 32u * pitch;
;                 u32x4 w[2];
; #pragma unroll
;                 for (int bj = 0; bj < 2; ++bj) { w[bj].x = cvtpk_h(v[bj][0][0], v[bj][0][1]); w[bj].y = cvtpk_h(v[bj][0][2], v[bj][0][3]); w[bj].z = cvtpk_h(v[bj][1][0], v[bj][1][1]); w[bj].w = cvtpk_h(v[bj][1][2], v[bj][1][3]); }
;                 stg_line_pair(wst, ro, 2u * pitch, w[0], w[1], odd);
;                 asm volatile("" ::: "memory"); }
.LBB0_591:
	v_cvt_pk_f16_f32 v152, v152, v153
	v_cvt_pk_f16_f32 v149, v148, v149
	v_cvt_pk_f16_f32 v150, v150, v151
	v_cvt_pk_f16_f32 v151, v158, v159
	v_mov_b32_e32 v148, v1
	v_mov_b32_e32 v158, v1
	v_cvt_pk_f16_f32 v153, v154, v155
	v_mov_b32_dpp v148, v149 quad_perm:[1,0,3,2] row_mask:0xf bank_mask:0xf
	v_mov_b32_dpp v158, v152 quad_perm:[1,0,3,2] row_mask:0xf bank_mask:0xf
	v_cndmask_b32_e64 v148, v148, v152, s[2:3]
	v_cndmask_b32_e64 v152, v149, v158, s[2:3]
	v_mov_b32_e32 v149, v1
	v_mov_b32_e32 v158, v1
	v_cvt_pk_f16_f32 v154, v180, v181
	v_mov_b32_dpp v149, v150 quad_perm:[1,0,3,2] row_mask:0xf bank_mask:0xf
	v_mov_b32_dpp v158, v153 quad_perm:[1,0,3,2] row_mask:0xf bank_mask:0xf
	v_cndmask_b32_e64 v149, v149, v153, s[2:3]
	v_cndmask_b32_e64 v153, v150, v158, s[2:3]
	v_mov_b32_e32 v150, v1
	v_mov_b32_e32 v158, v1
	v_cvt_pk_f16_f32 v156, v156, v157
	v_mov_b32_dpp v150, v151 quad_perm:[1,0,3,2] row_mask:0xf bank_mask:0xf
	v_mov_b32_dpp v158, v154 quad_perm:[1,0,3,2] row_mask:0xf bank_mask:0xf
	v_cndmask_b32_e64 v150, v150, v154, s[2:3]
	v_cndmask_b32_e64 v154, v151, v158, s[2:3]
	v_mov_b32_e32 v151, v1
	s_lshl_b32 s4, 0x160, s42
	v_cvt_pk_f16_f32 v155, v178, v179
	v_mov_b32_dpp v151, v156 quad_perm:[1,0,3,2] row_mask:0xf bank_mask:0xf
	v_mov_b32_e32 v158, v1
	v_add_u32_e32 v157, s4, v206
	v_cndmask_b32_e64 v151, v151, v155, s[2:3]
	v_mov_b32_dpp v158, v155 quad_perm:[1,0,3,2] row_mask:0xf bank_mask:0xf
	v_cndmask_b32_e64 v155, v156, v158, s[2:3]
	global_store_dwordx4 v157, v[148:151], s[36:37] sc1
	s_mov_b64 s[2:3], 0
	s_nop 0
	v_add_u32_e32 v148, s9, v157
	global_store_dwordx4 v148, v[152:155], s[36:37] sc1

; __device__ __forceinline__ unsigned cvtpk_h(float lo, float hi) { f32x2 v = {lo, hi}; h16x2 b = __builtin_convertvector(v, h16x2); return __builtin_bit_cast(unsigned, b); }
;     __device__ __forceinline__ void operator()(const f32x4 (&acc)[2][2][4][2], const pg8::Unit& u, int wr, int wc, int fr, int fq) const {
;     ...
;             const bool odd = (fr & 1) != 0;
;             const unsigned offA = base + ((row0 + (unsigned)(wr * 64 + (fr & ~1))) * pitch + coff) * 2u + (odd ? 64u : 0u) + 16u * fq;
; #pragma unroll
;             for (int ai = 0; ai < 2; ++ai)
; #pragma unroll
;                 for (int m = 0; m < 4; ++m) { const unsigned ro = offA + (unsigned)(ai * 8 + m) * rowstep; const float r = rs[ai][m];
;                     u32x4 w[2];
; #pragma unroll
;                     for (int bj = 0; bj < 2; ++bj) { const f32x4 v0 = acc[ai][bj][m][0] * r + bv[bj][0], v1 = acc[ai][bj][m][1] * r + bv[bj][1];
;                         w[bj].x = cvtpk_h(v0[0], v0[1]); w[bj].y = cvtpk_h(v0[2], v0[3]); w[bj].z = cvtpk_h(v1[0], v1[1]); w[bj].w = cvtpk_h(v1[2], v1[3]); }
;                     stg_line_pair(wst, ro, 2u * pitch, w[0], w[1], odd);
;                     asm volatile("" ::: "memory"); }
.LBB0_632:
	v_and_b32_e32 v178, 0x7ffffffe, v202
	s_add_i32 s2, s42, s77
	v_add_u32_e32 v178, s2, v178
	v_and_b32_e32 v186, 1, v202
	v_mul_lo_u32 v178, s9, v178
	v_add_lshl_u32 v178, v178, s38, 1
	v_lshl_add_u32 v179, v186, 6, v203
	v_pk_fma_f32 v[180:181], v[70:71], v[162:163], v[148:149] op_sel_hi:[1,0,1]
	s_waitcnt vmcnt(1)
	v_pk_fma_f32 v[128:129], v[128:129], v[162:163], v[142:143] op_sel_hi:[1,0,1]
	v_pk_fma_f32 v[126:127], v[126:127], v[162:163], v[140:141] op_sel_hi:[1,0,1]
	s_waitcnt vmcnt(0)
	v_pk_fma_f32 v[122:123], v[122:123], v[162:163], v[144:145] op_sel_hi:[1,0,1]
	v_add3_u32 v187, v179, s39, v178
	v_pk_fma_f32 v[178:179], v[72:73], v[162:163], v[150:151] op_sel_hi:[1,0,1]
	v_cvt_pk_f16_f32 v180, v180, v181
	v_pk_fma_f32 v[124:125], v[124:125], v[162:163], v[146:147] op_sel_hi:[1,0,1]
	v_cvt_pk_f16_f32 v126, v126, v127
	v_cvt_pk_f16_f32 v127, v128, v129
	v_cvt_pk_f16_f32 v128, v122, v123
	v_mov_b32_e32 v123, v1
	v_pk_fma_f32 v[184:185], v[66:67], v[162:163], v[152:153] op_sel_hi:[1,0,1]
	v_cvt_pk_f16_f32 v178, v178, v179
	v_cvt_pk_f16_f32 v129, v124, v125
	v_mov_b32_e32 v122, v1
	v_mov_b32_dpp v123, v180 quad_perm:[1,0,3,2] row_mask:0xf bank_mask:0xf
	v_cmp_eq_u32_e32 vcc, 0, v186
	v_mov_b32_e32 v124, v1
	v_cvt_pk_f16_f32 v179, v184, v185
	v_mov_b32_dpp v122, v126 quad_perm:[1,0,3,2] row_mask:0xf bank_mask:0xf
	v_cndmask_b32_e32 v126, v126, v123, vcc
	v_mov_b32_e32 v123, v1
	v_mov_b32_dpp v124, v178 quad_perm:[1,0,3,2] row_mask:0xf bank_mask:0xf
	v_mov_b32_e32 v125, v1
	v_mov_b32_dpp v123, v127 quad_perm:[1,0,3,2] row_mask:0xf bank_mask:0xf
	v_cndmask_b32_e32 v127, v127, v124, vcc
	v_mov_b32_e32 v124, v1
	v_mov_b32_dpp v125, v179 quad_perm:[1,0,3,2] row_mask:0xf bank_mask:0xf
	v_pk_fma_f32 v[182:183], v[68:69], v[162:163], v[154:155] op_sel_hi:[1,0,1]
	v_mov_b32_dpp v124, v128 quad_perm:[1,0,3,2] row_mask:0xf bank_mask:0xf
	v_cndmask_b32_e32 v128, v128, v125, vcc
	v_mov_b32_e32 v125, v1
	v_cvt_pk_f16_f32 v181, v182, v183
	v_cndmask_b32_e32 v123, v123, v178, vcc
	v_mov_b32_dpp v125, v129 quad_perm:[1,0,3,2] row_mask:0xf bank_mask:0xf
	v_mov_b32_e32 v178, v1
	s_lshl_b32 s2, s9, 1
	v_cndmask_b32_e32 v122, v122, v180, vcc
	v_cndmask_b32_e32 v124, v124, v179, vcc
	v_mov_b32_dpp v178, v181 quad_perm:[1,0,3,2] row_mask:0xf bank_mask:0xf
	v_cndmask_b32_e32 v125, v125, v181, vcc
	v_cndmask_b32_e32 v129, v129, v178, vcc
	global_store_dwordx4 v187, v[122:125], s[36:37] sc1
	v_pk_fma_f32 v[120:121], v[120:121], v[162:163], v[142:143] op_sel:[0,1,0]
	v_pk_fma_f32 v[118:119], v[118:119], v[162:163], v[140:141] op_sel:[0,1,0]
	v_add_u32_e32 v122, s2, v187
	global_store_dwordx4 v122, v[126:129], s[36:37] sc1
	v_pk_fma_f32 v[114:115], v[114:115], v[162:163], v[144:145] op_sel:[0,1,0]
	v_pk_fma_f32 v[124:125], v[52:53], v[162:163], v[150:151] op_sel:[0,1,0]
	v_pk_fma_f32 v[126:127], v[50:51], v[162:163], v[148:149] op_sel:[0,1,0]
	v_pk_fma_f32 v[116:117], v[116:117], v[162:163], v[146:147] op_sel:[0,1,0]
	v_cvt_pk_f16_f32 v126, v126, v127
	v_cvt_pk_f16_f32 v118, v118, v119
	v_cvt_pk_f16_f32 v119, v120, v121
	v_cvt_pk_f16_f32 v120, v114, v115
	v_mov_b32_e32 v115, v1
	v_pk_fma_f32 v[178:179], v[46:47], v[162:163], v[152:153] op_sel:[0,1,0]
	v_cvt_pk_f16_f32 v124, v124, v125
	v_cvt_pk_f16_f32 v121, v116, v117
	v_mov_b32_e32 v114, v1
	v_mov_b32_dpp v115, v126 quad_perm:[1,0,3,2] row_mask:0xf bank_mask:0xf
	v_mov_b32_e32 v116, v1
	v_cvt_pk_f16_f32 v125, v178, v179
	v_mov_b32_dpp v114, v118 quad_perm:[1,0,3,2] row_mask:0xf bank_mask:0xf
	v_cndmask_b32_e32 v118, v118, v115, vcc
	v_mov_b32_e32 v115, v1
	v_mov_b32_dpp v116, v124 quad_perm:[1,0,3,2] row_mask:0xf bank_mask:0xf
	v_mov_b32_e32 v117, v1
	v_mov_b32_dpp v115, v119 quad_perm:[1,0,3,2] row_mask:0xf bank_mask:0xf
	v_cndmask_b32_e32 v119, v119, v116, vcc
	v_mov_b32_e32 v116, v1
	v_mov_b32_dpp v117, v125 quad_perm:[1,0,3,2] row_mask:0xf bank_mask:0xf
	v_pk_fma_f32 v[128:129], v[48:49], v[162:163], v[154:155] op_sel:[0,1,0]
	v_mad_u64_u32 v[122:123], s[4:5], s9, 30, v[122:123]
	v_mov_b32_dpp v116, v120 quad_perm:[1,0,3,2] row_mask:0xf bank_mask:0xf
	v_cndmask_b32_e32 v120, v120, v117, vcc
	v_mov_b32_e32 v117, v1
	v_cvt_pk_f16_f32 v127, v128, v129
	v_mov_b32_e32 v123, v1
	v_mov_b32_dpp v117, v121 quad_perm:[1,0,3,2] row_mask:0xf bank_mask:0xf
	v_cndmask_b32_e32 v114, v114, v126, vcc
	v_cndmask_b32_e32 v115, v115, v124, vcc
	v_cndmask_b32_e32 v116, v116, v125, vcc
	v_mov_b32_dpp v123, v127 quad_perm:[1,0,3,2] row_mask:0xf bank_mask:0xf
	v_cndmask_b32_e32 v117, v117, v127, vcc
	v_cndmask_b32_e32 v121, v121, v123, vcc
	global_store_dwordx4 v122, v[114:117], s[36:37] sc1
	v_pk_fma_f32 v[112:113], v[112:113], v[160:161], v[142:143] op_sel_hi:[1,0,1]
	v_pk_fma_f32 v[110:111], v[110:111], v[160:161], v[140:141] op_sel_hi:[1,0,1]
	v_add_u32_e32 v114, s2, v122
	v_pk_fma_f32 v[116:117], v[54:55], v[160:161], v[148:149] op_sel_hi:[1,0,1]
	v_pk_fma_f32 v[106:107], v[106:107], v[160:161], v[144:145] op_sel_hi:[1,0,1]
	global_store_dwordx4 v114, v[118:121], s[36:37] sc1
	v_pk_fma_f32 v[114:115], v[56:57], v[160:161], v[150:151] op_sel_hi:[1,0,1]
	v_cvt_pk_f16_f32 v116, v116, v117
	v_pk_fma_f32 v[108:109], v[108:109], v[160:161], v[146:147] op_sel_hi:[1,0,1]
	v_cvt_pk_f16_f32 v110, v110, v111
	v_cvt_pk_f16_f32 v111, v112, v113
	v_cvt_pk_f16_f32 v112, v106, v107
	v_mov_b32_e32 v107, v1
	v_pk_fma_f32 v[120:121], v[42:43], v[160:161], v[152:153] op_sel_hi:[1,0,1]
	v_cvt_pk_f16_f32 v114, v114, v115
	v_cvt_pk_f16_f32 v113, v108, v109
	v_mov_b32_e32 v106, v1
	v_mov_b32_dpp v107, v116 quad_perm:[1,0,3,2] row_mask:0xf bank_mask:0xf
	v_mov_b32_e32 v108, v1
	v_cvt_pk_f16_f32 v115, v120, v121
; __device__ __forceinline__ unsigned cvtpk_h(float lo, float hi) { f32x2 v = {lo, hi}; h16x2 b = __builtin_convertvector(v, h16x2); return __builtin_bit_cast(unsigned, b); }
;     __device__ __forceinline__ void operator()(const f32x4 (&acc)[2][2][4][2], const pg8::Unit& u, int wr, int wc, int fr, int fq) const {
;     ...
;             for (int ai = 0; ai < 2; ++ai)
; #pragma unroll
;                 for (int m = 0; m < 4; ++m) { const unsigned ro = offA + (unsigned)(ai * 8 + m) * rowstep; const float r = rs[ai][m];
;                     u32x4 w[2];
; #pragma unroll
;                     for (int bj = 0; bj < 2; ++bj) { const f32x4 v0 = acc[ai][bj][m][0] * r + bv[bj][0], v1 = acc[ai][bj][m][1] * r + bv[bj][1];
;                         w[bj].x = cvtpk_h(v0[0], v0[1]); w[bj].y = cvtpk_h(v0[2], v0[3]); w[bj].z = cvtpk_h(v1[0], v1[1]); w[bj].w = cvtpk_h(v1[2], v1[3]); }
;                     stg_line_pair(wst, ro, 2u * pitch, w[0], w[1], odd);
;                     asm volatile("" ::: "memory"); }
	v_mov_b32_dpp v106, v110 quad_perm:[1,0,3,2] row_mask:0xf bank_mask:0xf
	v_cndmask_b32_e32 v110, v110, v107, vcc
	v_mov_b32_e32 v107, v1
	v_mov_b32_dpp v108, v114 quad_perm:[1,0,3,2] row_mask:0xf bank_mask:0xf
	v_mov_b32_e32 v109, v1
	v_mov_b32_dpp v107, v111 quad_perm:[1,0,3,2] row_mask:0xf bank_mask:0xf
	v_cndmask_b32_e32 v111, v111, v108, vcc
	v_mov_b32_e32 v108, v1
	v_mov_b32_dpp v109, v115 quad_perm:[1,0,3,2] row_mask:0xf bank_mask:0xf
	v_pk_fma_f32 v[118:119], v[44:45], v[160:161], v[154:155] op_sel_hi:[1,0,1]
	v_mov_b32_dpp v108, v112 quad_perm:[1,0,3,2] row_mask:0xf bank_mask:0xf
	v_cndmask_b32_e32 v112, v112, v109, vcc
	v_mov_b32_e32 v109, v1
	v_cvt_pk_f16_f32 v117, v118, v119
	s_lshl_b32 s3, s9, 5
	v_cndmask_b32_e32 v107, v107, v114, vcc
	v_mov_b32_dpp v109, v113 quad_perm:[1,0,3,2] row_mask:0xf bank_mask:0xf
	v_mov_b32_e32 v114, v1
	v_add_u32_e32 v118, s3, v122
	v_cndmask_b32_e32 v106, v106, v116, vcc
	v_cndmask_b32_e32 v108, v108, v115, vcc
	v_mov_b32_dpp v114, v117 quad_perm:[1,0,3,2] row_mask:0xf bank_mask:0xf
	v_cndmask_b32_e32 v109, v109, v117, vcc
	v_cndmask_b32_e32 v113, v113, v114, vcc
	global_store_dwordx4 v118, v[106:109], s[36:37] sc1
	v_pk_fma_f32 v[104:105], v[104:105], v[160:161], v[142:143] op_sel:[0,1,0]
	v_pk_fma_f32 v[102:103], v[102:103], v[160:161], v[140:141] op_sel:[0,1,0]
	v_add_u32_e32 v106, s2, v118
	v_pk_fma_f32 v[108:109], v[38:39], v[160:161], v[148:149] op_sel:[0,1,0]
	v_pk_fma_f32 v[98:99], v[98:99], v[160:161], v[144:145] op_sel:[0,1,0]
	global_store_dwordx4 v106, v[110:113], s[36:37] sc1
	v_pk_fma_f32 v[106:107], v[40:41], v[160:161], v[150:151] op_sel:[0,1,0]
	v_cvt_pk_f16_f32 v108, v108, v109
	v_pk_fma_f32 v[100:101], v[100:101], v[160:161], v[146:147] op_sel:[0,1,0]
	v_cvt_pk_f16_f32 v102, v102, v103
	v_cvt_pk_f16_f32 v103, v104, v105
	v_cvt_pk_f16_f32 v104, v98, v99
	v_mov_b32_e32 v99, v1
	v_pk_fma_f32 v[112:113], v[34:35], v[160:161], v[152:153] op_sel:[0,1,0]
	v_cvt_pk_f16_f32 v106, v106, v107
	v_cvt_pk_f16_f32 v105, v100, v101
	v_mov_b32_e32 v98, v1
	v_mov_b32_dpp v99, v108 quad_perm:[1,0,3,2] row_mask:0xf bank_mask:0xf
	v_mov_b32_e32 v100, v1
	v_cvt_pk_f16_f32 v107, v112, v113
	v_mov_b32_dpp v98, v102 quad_perm:[1,0,3,2] row_mask:0xf bank_mask:0xf
	v_cndmask_b32_e32 v102, v102, v99, vcc
	v_mov_b32_e32 v99, v1
	v_mov_b32_dpp v100, v106 quad_perm:[1,0,3,2] row_mask:0xf bank_mask:0xf
	v_mov_b32_e32 v101, v1
	v_mov_b32_dpp v99, v103 quad_perm:[1,0,3,2] row_mask:0xf bank_mask:0xf
	v_cndmask_b32_e32 v103, v103, v100, vcc
	v_mov_b32_e32 v100, v1
	v_mov_b32_dpp v101, v107 quad_perm:[1,0,3,2] row_mask:0xf bank_mask:0xf
	v_pk_fma_f32 v[110:111], v[36:37], v[160:161], v[154:155] op_sel:[0,1,0]
	v_mov_b32_dpp v100, v104 quad_perm:[1,0,3,2] row_mask:0xf bank_mask:0xf
	v_cndmask_b32_e32 v104, v104, v101, vcc
	v_mov_b32_e32 v101, v1
	v_cvt_pk_f16_f32 v109, v110, v111
	v_cndmask_b32_e32 v99, v99, v106, vcc
	v_mov_b32_dpp v101, v105 quad_perm:[1,0,3,2] row_mask:0xf bank_mask:0xf
	v_mov_b32_e32 v106, v1
	v_add_u32_e32 v110, s3, v118
	v_cndmask_b32_e32 v98, v98, v108, vcc
	v_cndmask_b32_e32 v100, v100, v107, vcc
	v_mov_b32_dpp v106, v109 quad_perm:[1,0,3,2] row_mask:0xf bank_mask:0xf
	v_cndmask_b32_e32 v101, v101, v109, vcc
	v_cndmask_b32_e32 v105, v105, v106, vcc
	global_store_dwordx4 v110, v[98:101], s[36:37] sc1
	v_pk_fma_f32 v[96:97], v[96:97], v[158:159], v[142:143] op_sel_hi:[1,0,1]
	v_pk_fma_f32 v[94:95], v[94:95], v[158:159], v[140:141] op_sel_hi:[1,0,1]
	v_add_u32_e32 v98, s2, v110
	v_pk_fma_f32 v[100:101], v[30:31], v[158:159], v[148:149] op_sel_hi:[1,0,1]
	v_pk_fma_f32 v[90:91], v[90:91], v[158:159], v[144:145] op_sel_hi:[1,0,1]
	global_store_dwordx4 v98, v[102:105], s[36:37] sc1
	v_pk_fma_f32 v[98:99], v[32:33], v[158:159], v[150:151] op_sel_hi:[1,0,1]
	v_cvt_pk_f16_f32 v100, v100, v101
	v_pk_fma_f32 v[92:93], v[92:93], v[158:159], v[146:147] op_sel_hi:[1,0,1]
	v_cvt_pk_f16_f32 v94, v94, v95
	v_cvt_pk_f16_f32 v95, v96, v97
	v_cvt_pk_f16_f32 v96, v90, v91
	v_mov_b32_e32 v91, v1
	v_pk_fma_f32 v[104:105], v[26:27], v[158:159], v[152:153] op_sel_hi:[1,0,1]
	v_cvt_pk_f16_f32 v98, v98, v99
	v_cvt_pk_f16_f32 v97, v92, v93
	v_mov_b32_e32 v90, v1
	v_mov_b32_dpp v91, v100 quad_perm:[1,0,3,2] row_mask:0xf bank_mask:0xf
	v_mov_b32_e32 v92, v1
	v_cvt_pk_f16_f32 v99, v104, v105
	v_mov_b32_dpp v90, v94 quad_perm:[1,0,3,2] row_mask:0xf bank_mask:0xf
	v_cndmask_b32_e32 v94, v94, v91, vcc
	v_mov_b32_e32 v91, v1
	v_mov_b32_dpp v92, v98 quad_perm:[1,0,3,2] row_mask:0xf bank_mask:0xf
	v_mov_b32_e32 v93, v1
	v_mov_b32_dpp v91, v95 quad_perm:[1,0,3,2] row_mask:0xf bank_mask:0xf
	v_cndmask_b32_e32 v95, v95, v92, vcc
	v_mov_b32_e32 v92, v1
	v_mov_b32_dpp v93, v99 quad_perm:[1,0,3,2] row_mask:0xf bank_mask:0xf
	v_pk_fma_f32 v[102:103], v[28:29], v[158:159], v[154:155] op_sel_hi:[1,0,1]
	v_mov_b32_dpp v92, v96 quad_perm:[1,0,3,2] row_mask:0xf bank_mask:0xf
	v_cndmask_b32_e32 v96, v96, v93, vcc
	v_mov_b32_e32 v93, v1
	v_cvt_pk_f16_f32 v101, v102, v103
	s_mul_i32 s4, s9, 0xa0
	v_cndmask_b32_e32 v91, v91, v98, vcc
	v_mov_b32_dpp v93, v97 quad_perm:[1,0,3,2] row_mask:0xf bank_mask:0xf
	v_mov_b32_e32 v98, v1
	v_add_u32_e32 v102, s4, v110
	v_cndmask_b32_e32 v90, v90, v100, vcc
	v_cndmask_b32_e32 v92, v92, v99, vcc
	v_mov_b32_dpp v98, v101 quad_perm:[1,0,3,2] row_mask:0xf bank_mask:0xf
	v_cndmask_b32_e32 v93, v93, v101, vcc
	v_cndmask_b32_e32 v97, v97, v98, vcc
	global_store_dwordx4 v102, v[90:93], s[36:37] sc1
	v_pk_fma_f32 v[88:89], v[88:89], v[158:159], v[142:143] op_sel:[0,1,0]
	v_pk_fma_f32 v[86:87], v[86:87], v[158:159], v[140:141] op_sel:[0,1,0]
	v_add_u32_e32 v90, s2, v102
	v_pk_fma_f32 v[92:93], v[22:23], v[158:159], v[148:149] op_sel:[0,1,0]
; __device__ __forceinline__ unsigned cvtpk_h(float lo, float hi) { f32x2 v = {lo, hi}; h16x2 b = __builtin_convertvector(v, h16x2); return __builtin_bit_cast(unsigned, b); }
;     __device__ __forceinline__ void operator()(const f32x4 (&acc)[2][2][4][2], const pg8::Unit& u, int wr, int wc, int fr, int fq) const {
;     ...
;             for (int ai = 0; ai < 2; ++ai)
; #pragma unroll
;                 for (int m = 0; m < 4; ++m) { const unsigned ro = offA + (unsigned)(ai * 8 + m) * rowstep; const float r = rs[ai][m];
;                     u32x4 w[2];
; #pragma unroll
;                     for (int bj = 0; bj < 2; ++bj) { const f32x4 v0 = acc[ai][bj][m][0] * r + bv[bj][0], v1 = acc[ai][bj][m][1] * r + bv[bj][1];
;                         w[bj].x = cvtpk_h(v0[0], v0[1]); w[bj].y = cvtpk_h(v0[2], v0[3]); w[bj].z = cvtpk_h(v1[0], v1[1]); w[bj].w = cvtpk_h(v1[2], v1[3]); }
;                     stg_line_pair(wst, ro, 2u * pitch, w[0], w[1], odd);
;                     asm volatile("" ::: "memory"); }
	v_pk_fma_f32 v[82:83], v[82:83], v[158:159], v[144:145] op_sel:[0,1,0]
	global_store_dwordx4 v90, v[94:97], s[36:37] sc1
	v_pk_fma_f32 v[90:91], v[24:25], v[158:159], v[150:151] op_sel:[0,1,0]
	v_cvt_pk_f16_f32 v92, v92, v93
	v_pk_fma_f32 v[84:85], v[84:85], v[158:159], v[146:147] op_sel:[0,1,0]
	v_cvt_pk_f16_f32 v86, v86, v87
	v_cvt_pk_f16_f32 v87, v88, v89
	v_cvt_pk_f16_f32 v88, v82, v83
	v_mov_b32_e32 v83, v1
	v_pk_fma_f32 v[96:97], v[18:19], v[158:159], v[152:153] op_sel:[0,1,0]
	v_cvt_pk_f16_f32 v90, v90, v91
	v_cvt_pk_f16_f32 v89, v84, v85
	v_mov_b32_e32 v82, v1
	v_mov_b32_dpp v83, v92 quad_perm:[1,0,3,2] row_mask:0xf bank_mask:0xf
	v_mov_b32_e32 v84, v1
	v_cvt_pk_f16_f32 v91, v96, v97
	v_mov_b32_dpp v82, v86 quad_perm:[1,0,3,2] row_mask:0xf bank_mask:0xf
	v_cndmask_b32_e32 v86, v86, v83, vcc
	v_mov_b32_e32 v83, v1
	v_mov_b32_dpp v84, v90 quad_perm:[1,0,3,2] row_mask:0xf bank_mask:0xf
	v_mov_b32_e32 v85, v1
	v_mov_b32_dpp v83, v87 quad_perm:[1,0,3,2] row_mask:0xf bank_mask:0xf
	v_cndmask_b32_e32 v87, v87, v84, vcc
	v_mov_b32_e32 v84, v1
	v_mov_b32_dpp v85, v91 quad_perm:[1,0,3,2] row_mask:0xf bank_mask:0xf
	v_pk_fma_f32 v[94:95], v[20:21], v[158:159], v[154:155] op_sel:[0,1,0]
	v_mov_b32_dpp v84, v88 quad_perm:[1,0,3,2] row_mask:0xf bank_mask:0xf
	v_cndmask_b32_e32 v88, v88, v85, vcc
	v_mov_b32_e32 v85, v1
	v_cvt_pk_f16_f32 v93, v94, v95
	v_cndmask_b32_e32 v83, v83, v90, vcc
	v_mov_b32_dpp v85, v89 quad_perm:[1,0,3,2] row_mask:0xf bank_mask:0xf
	v_mov_b32_e32 v90, v1
	v_add_u32_e32 v94, s3, v102
	v_cndmask_b32_e32 v82, v82, v92, vcc
	v_cndmask_b32_e32 v84, v84, v91, vcc
	v_mov_b32_dpp v90, v93 quad_perm:[1,0,3,2] row_mask:0xf bank_mask:0xf
	v_cndmask_b32_e32 v85, v85, v93, vcc
	v_cndmask_b32_e32 v89, v89, v90, vcc
	global_store_dwordx4 v94, v[82:85], s[36:37] sc1
	v_pk_fma_f32 v[80:81], v[80:81], v[156:157], v[142:143] op_sel_hi:[1,0,1]
	v_pk_fma_f32 v[78:79], v[78:79], v[156:157], v[140:141] op_sel_hi:[1,0,1]
	v_add_u32_e32 v82, s2, v94
	v_pk_fma_f32 v[84:85], v[14:15], v[156:157], v[148:149] op_sel_hi:[1,0,1]
	v_pk_fma_f32 v[74:75], v[74:75], v[156:157], v[144:145] op_sel_hi:[1,0,1]
	global_store_dwordx4 v82, v[86:89], s[36:37] sc1
	v_pk_fma_f32 v[82:83], v[16:17], v[156:157], v[150:151] op_sel_hi:[1,0,1]
	v_cvt_pk_f16_f32 v84, v84, v85
	v_pk_fma_f32 v[76:77], v[76:77], v[156:157], v[146:147] op_sel_hi:[1,0,1]
	v_cvt_pk_f16_f32 v78, v78, v79
	v_cvt_pk_f16_f32 v79, v80, v81
	v_cvt_pk_f16_f32 v80, v74, v75
	v_mov_b32_e32 v75, v1
	v_pk_fma_f32 v[88:89], v[10:11], v[156:157], v[152:153] op_sel_hi:[1,0,1]
	v_cvt_pk_f16_f32 v82, v82, v83
	v_cvt_pk_f16_f32 v81, v76, v77
	v_mov_b32_e32 v74, v1
	v_mov_b32_dpp v75, v84 quad_perm:[1,0,3,2] row_mask:0xf bank_mask:0xf
	v_mov_b32_e32 v76, v1
	v_cvt_pk_f16_f32 v83, v88, v89
	v_mov_b32_dpp v74, v78 quad_perm:[1,0,3,2] row_mask:0xf bank_mask:0xf
	v_cndmask_b32_e32 v78, v78, v75, vcc
	v_mov_b32_e32 v75, v1
	v_mov_b32_dpp v76, v82 quad_perm:[1,0,3,2] row_mask:0xf bank_mask:0xf
	v_mov_b32_e32 v77, v1
	v_mov_b32_dpp v75, v79 quad_perm:[1,0,3,2] row_mask:0xf bank_mask:0xf
	v_cndmask_b32_e32 v79, v79, v76, vcc
	v_mov_b32_e32 v76, v1
	v_mov_b32_dpp v77, v83 quad_perm:[1,0,3,2] row_mask:0xf bank_mask:0xf
	v_pk_fma_f32 v[86:87], v[12:13], v[156:157], v[154:155] op_sel_hi:[1,0,1]
	v_mov_b32_dpp v76, v80 quad_perm:[1,0,3,2] row_mask:0xf bank_mask:0xf
	v_cndmask_b32_e32 v80, v80, v77, vcc
	v_mov_b32_e32 v77, v1
	v_cvt_pk_f16_f32 v85, v86, v87
	v_cndmask_b32_e32 v75, v75, v82, vcc
	v_mov_b32_dpp v77, v81 quad_perm:[1,0,3,2] row_mask:0xf bank_mask:0xf
	v_mov_b32_e32 v82, v1
	v_add_u32_e32 v86, s3, v94
	v_cndmask_b32_e32 v74, v74, v84, vcc
	v_cndmask_b32_e32 v76, v76, v83, vcc
	v_mov_b32_dpp v82, v85 quad_perm:[1,0,3,2] row_mask:0xf bank_mask:0xf
	v_cndmask_b32_e32 v77, v77, v85, vcc
	v_cndmask_b32_e32 v81, v81, v82, vcc
	global_store_dwordx4 v86, v[74:77], s[36:37] sc1
	v_pk_fma_f32 v[64:65], v[64:65], v[156:157], v[142:143] op_sel:[0,1,0]
	v_pk_fma_f32 v[62:63], v[62:63], v[156:157], v[140:141] op_sel:[0,1,0]
	v_add_u32_e32 v74, s2, v86
	v_pk_fma_f32 v[76:77], v[6:7], v[156:157], v[148:149] op_sel:[0,1,0]
	v_pk_fma_f32 v[58:59], v[58:59], v[156:157], v[144:145] op_sel:[0,1,0]
	global_store_dwordx4 v74, v[78:81], s[36:37] sc1
	v_pk_fma_f32 v[74:75], v[8:9], v[156:157], v[150:151] op_sel:[0,1,0]
	v_cvt_pk_f16_f32 v76, v76, v77
	v_pk_fma_f32 v[60:61], v[60:61], v[156:157], v[146:147] op_sel:[0,1,0]
	v_cvt_pk_f16_f32 v62, v62, v63
	v_cvt_pk_f16_f32 v63, v64, v65
	v_cvt_pk_f16_f32 v64, v58, v59
	v_mov_b32_e32 v59, v1
	v_pk_fma_f32 v[80:81], v[2:3], v[156:157], v[152:153] op_sel:[0,1,0]
	v_cvt_pk_f16_f32 v74, v74, v75
	v_cvt_pk_f16_f32 v65, v60, v61
	v_mov_b32_e32 v58, v1
	v_mov_b32_dpp v59, v76 quad_perm:[1,0,3,2] row_mask:0xf bank_mask:0xf
	v_mov_b32_e32 v60, v1
	v_cvt_pk_f16_f32 v75, v80, v81
	v_mov_b32_dpp v58, v62 quad_perm:[1,0,3,2] row_mask:0xf bank_mask:0xf
	v_cndmask_b32_e32 v62, v62, v59, vcc
	v_mov_b32_e32 v59, v1
	v_mov_b32_dpp v60, v74 quad_perm:[1,0,3,2] row_mask:0xf bank_mask:0xf
	v_mov_b32_e32 v61, v1
	v_mov_b32_dpp v59, v63 quad_perm:[1,0,3,2] row_mask:0xf bank_mask:0xf
	v_cndmask_b32_e32 v63, v63, v60, vcc
	v_mov_b32_e32 v60, v1
	v_mov_b32_dpp v61, v75 quad_perm:[1,0,3,2] row_mask:0xf bank_mask:0xf
	v_pk_fma_f32 v[78:79], v[4:5], v[156:157], v[154:155] op_sel:[0,1,0]
	v_mov_b32_dpp v60, v64 quad_perm:[1,0,3,2] row_mask:0xf bank_mask:0xf
	v_cndmask_b32_e32 v64, v64, v61, vcc
	v_mov_b32_e32 v61, v1
	v_cvt_pk_f16_f32 v77, v78, v79
	v_cndmask_b32_e32 v59, v59, v74, vcc
	v_mov_b32_dpp v61, v65 quad_perm:[1,0,3,2] row_mask:0xf bank_mask:0xf
	v_mov_b32_e32 v74, v1
	v_add_u32_e32 v78, s3, v86
	v_cndmask_b32_e32 v58, v58, v76, vcc
	v_cndmask_b32_e32 v60, v60, v75, vcc
	v_mov_b32_dpp v74, v77 quad_perm:[1,0,3,2] row_mask:0xf bank_mask:0xf
	v_cndmask_b32_e32 v61, v61, v77, vcc
	v_cndmask_b32_e32 v65, v65, v74, vcc
	global_store_dwordx4 v78, v[58:61], s[36:37] sc1
	s_nop 1
	v_add_u32_e32 v58, s2, v78
	global_store_dwordx4 v58, v[62:65], s[36:37] sc1
	s_mov_b64 s[2:3], 0
; #define GAS __attribute__((address_space(1)))
; __device__ __forceinline__ float logsigf(float x) { return fminf(x, 0.f) - 0.6931471805599453f * __builtin_amdgcn_logf(1.f + __builtin_amdgcn_exp2f(-1.4426950408889634f * fabsf(x))); }
;     __device__ __forceinline__ void operator()(const f32x4 (&acc)[2][2][4][2], const pg8::Unit& u, int wr, int wc, int fr, int fq) const {
;     ...
;             if (s == 52) {
;                 if (fq < 2) { const f32x4 g0 = *(const GAS f32x4*)(bg + 8 * fq), g1 = *(const GAS f32x4*)(bg + 8 * fq + 4);
; #pragma unroll
;                     for (int ai = 0; ai < 2; ++ai)
; #pragma unroll
;                         for (int m = 0; m < 4; ++m) { const float r = rs[ai][m]; const f32x4 vi = acc[ai][0][m][0] * r + bv[0][0] + g0; f32x4 vf = acc[ai][0][m][1] * r + bv[0][1] + g1;
;                             vf = (f32x4){logsigf(vf[0]), logsigf(vf[1]), logsigf(vf[2]), logsigf(vf[3])};
;                             const unsigned go = (unsigned)WS_G + (rbase + ai * 128 + m * 16) * 64u + 32u * fq; stg_f4(wst, go, vi); stg_f4(wst, go + 16u, vf); } }
;                 return;
.LBB0_633:
	s_and_b64 vcc, exec, s[2:3]
	s_cbranch_vccz .LBB0_637
	v_cmp_gt_i32_e32 vcc, 2, v200
	s_and_saveexec_b64 s[2:3], vcc
	s_cbranch_execz .LBB0_636
	v_lshlrev_b32_e32 v58, 3, v200
	v_readlane_b32 s4, v253, 5
	v_ashrrev_i32_e32 v59, 31, v58
	v_readlane_b32 s5, v253, 6
	v_lshlrev_b32_e32 v75, 6, v201
	s_waitcnt vmcnt(2)
	v_pk_fma_f32 v[68:69], v[68:69], v[176:177], v[134:135] op_sel_hi:[1,0,1]
	v_lshl_add_u64 v[58:59], v[58:59], 2, s[4:5]
	global_load_dwordx4 v[62:65], v[58:59], off
	s_nop 0
	global_load_dwordx4 v[58:61], v[58:59], off offset:16
	v_pk_fma_f32 v[66:67], v[66:67], v[176:177], v[132:133] op_sel_hi:[1,0,1]
	v_mov_b32_e32 v74, v177
	v_pk_fma_f32 v[72:73], v[72:73], v[176:177], v[138:139] op_sel_hi:[1,0,1]
	v_pk_fma_f32 v[70:71], v[70:71], v[176:177], v[136:137] op_sel_hi:[1,0,1]
	v_pk_fma_f32 v[56:57], v[56:57], v[174:175], v[138:139] op_sel_hi:[1,0,1]
	v_pk_fma_f32 v[54:55], v[54:55], v[174:175], v[136:137] op_sel_hi:[1,0,1]
	v_pk_fma_f32 v[76:77], v[44:45], v[174:175], v[134:135] op_sel_hi:[1,0,1]
	v_pk_fma_f32 v[78:79], v[42:43], v[174:175], v[132:133] op_sel_hi:[1,0,1]
	v_lshl_add_u32 v82, v200, 5, v75
	v_pk_fma_f32 v[52:53], v[52:53], v[74:75], v[138:139] op_sel_hi:[1,0,1]
	v_pk_fma_f32 v[50:51], v[50:51], v[74:75], v[136:137] op_sel_hi:[1,0,1]
	v_pk_fma_f32 v[80:81], v[48:49], v[74:75], v[134:135] op_sel_hi:[1,0,1]
	v_pk_fma_f32 v[74:75], v[46:47], v[74:75], v[132:133] op_sel_hi:[1,0,1]
	s_mov_b32 s4, 0xbfb8aa3b
	v_add_u32_e32 v83, 0x2b00000, v82
	v_add_u32_e32 v84, 0x2b00400, v82
	s_mov_b32 s8, 0x3f317218
	v_pk_fma_f32 v[26:27], v[26:27], v[172:173], v[132:133] op_sel_hi:[1,0,1]
	v_pk_fma_f32 v[28:29], v[28:29], v[172:173], v[134:135] op_sel_hi:[1,0,1]
	v_pk_fma_f32 v[32:33], v[32:33], v[172:173], v[138:139] op_sel_hi:[1,0,1]
	v_pk_fma_f32 v[30:31], v[30:31], v[172:173], v[136:137] op_sel_hi:[1,0,1]
	v_pk_fma_f32 v[10:11], v[10:11], v[170:171], v[132:133] op_sel_hi:[1,0,1]
	v_pk_fma_f32 v[12:13], v[12:13], v[170:171], v[134:135] op_sel_hi:[1,0,1]
	v_pk_fma_f32 v[16:17], v[16:17], v[170:171], v[138:139] op_sel_hi:[1,0,1]
	v_pk_fma_f32 v[14:15], v[14:15], v[170:171], v[136:137] op_sel_hi:[1,0,1]
	s_waitcnt vmcnt(1)
	v_pk_add_f32 v[44:45], v[72:73], v[64:65]
	s_waitcnt vmcnt(0)
	v_pk_add_f32 v[68:69], v[68:69], v[60:61]
	v_pk_add_f32 v[66:67], v[66:67], v[58:59]
	v_pk_add_f32 v[42:43], v[70:71], v[62:63]
	v_pk_add_f32 v[48:49], v[52:53], v[64:65]
	v_pk_add_f32 v[46:47], v[50:51], v[62:63]
	v_pk_add_f32 v[70:71], v[80:81], v[60:61]
	v_pk_add_f32 v[72:73], v[74:75], v[58:59]
	v_pk_add_f32 v[52:53], v[56:57], v[64:65]
	v_pk_add_f32 v[50:51], v[54:55], v[62:63]
	v_pk_add_f32 v[54:55], v[76:77], v[60:61]
	v_pk_add_f32 v[56:57], v[78:79], v[58:59]
	v_mul_f32_e64 v76, |v66|, s4
	v_mul_f32_e64 v77, |v67|, s4
	v_mul_f32_e64 v78, |v68|, s4
	v_mul_f32_e64 v79, |v69|, s4
	v_min_f32_e32 v74, 0, v66
	v_min_f32_e32 v66, 0, v68
	global_store_dwordx4 v83, v[42:45], s[36:37] sc1
	v_min_f32_e32 v68, 0, v72
	global_store_dwordx4 v84, v[46:49], s[36:37] sc1
	v_mul_f32_e64 v42, |v72|, s4
	v_mul_f32_e64 v43, |v73|, s4
	v_min_f32_e32 v72, 0, v70
	v_mul_f32_e64 v44, |v70|, s4
	v_mul_f32_e64 v45, |v71|, s4
	v_min_f32_e32 v70, 0, v56
	v_mul_f32_e64 v46, |v56|, s4
	v_exp_f32_e32 v47, v76
	v_exp_f32_e32 v48, v77
	v_exp_f32_e32 v49, v78
	v_exp_f32_e32 v56, v79
	v_exp_f32_e32 v42, v42
	v_exp_f32_e32 v43, v43
	v_exp_f32_e32 v44, v44
	v_exp_f32_e32 v45, v45
	v_exp_f32_e32 v46, v46
	v_add_f32_e32 v47, 1.0, v47
	v_add_f32_e32 v48, 1.0, v48
	v_add_f32_e32 v49, 1.0, v49
	v_add_f32_e32 v56, 1.0, v56
	v_min_f32_e32 v75, 0, v67
	v_min_f32_e32 v67, 0, v69
	v_min_f32_e32 v69, 0, v73
	v_min_f32_e32 v73, 0, v71
	v_min_f32_e32 v71, 0, v57
	v_mul_f32_e64 v80, |v57|, s4
	v_add_f32_e32 v42, 1.0, v42
	v_add_f32_e32 v43, 1.0, v43
	v_add_f32_e32 v44, 1.0, v44
	v_add_f32_e32 v45, 1.0, v45
	v_log_f32_e32 v57, v47
	v_log_f32_e32 v47, v48
	v_log_f32_e32 v48, v49
	v_log_f32_e32 v49, v56
	v_log_f32_e32 v56, v42
	v_log_f32_e32 v76, v43
	v_log_f32_e32 v44, v44
	v_log_f32_e32 v45, v45
	v_add_f32_e32 v46, 1.0, v46
	v_log_f32_e32 v77, v46
	v_xor_b32_e32 v43, 0x80000000, v49
	v_xor_b32_e32 v42, 0x80000000, v48
	v_xor_b32_e32 v47, 0x80000000, v47
	v_xor_b32_e32 v46, 0x80000000, v57
	v_xor_b32_e32 v49, 0x80000000, v45
	v_xor_b32_e32 v48, 0x80000000, v44
	v_xor_b32_e32 v57, 0x80000000, v76
	v_xor_b32_e32 v56, 0x80000000, v56
	v_pk_fma_f32 v[44:45], v[42:43], s[8:9], v[66:67] op_sel_hi:[1,0,1]
	v_pk_fma_f32 v[42:43], v[46:47], s[8:9], v[74:75] op_sel_hi:[1,0,1]
	v_pk_fma_f32 v[48:49], v[48:49], s[8:9], v[72:73] op_sel_hi:[1,0,1]
	v_pk_fma_f32 v[46:47], v[56:57], s[8:9], v[68:69] op_sel_hi:[1,0,1]
	global_store_dwordx4 v83, v[42:45], s[36:37] offset:16 sc1
	global_store_dwordx4 v84, v[46:49], s[36:37] offset:16 sc1
	v_pk_add_f32 v[26:27], v[26:27], v[58:59]
	v_exp_f32_e32 v42, v80
	v_mul_f32_e64 v43, |v54|, s4
	v_mul_f32_e64 v44, |v55|, s4
	v_exp_f32_e32 v43, v43
	v_exp_f32_e32 v44, v44
	v_add_f32_e32 v42, 1.0, v42
	v_log_f32_e32 v46, v42
	v_add_f32_e32 v42, 1.0, v43
	v_add_f32_e32 v43, 1.0, v44
	v_log_f32_e32 v44, v43
	v_log_f32_e32 v47, v42
	v_min_f32_e32 v42, 0, v54
	v_min_f32_e32 v43, 0, v55
	v_xor_b32_e32 v45, 0x80000000, v44
	v_xor_b32_e32 v44, 0x80000000, v47
	v_pk_fma_f32 v[44:45], v[44:45], s[8:9], v[42:43] op_sel_hi:[1,0,1]
	v_xor_b32_e32 v43, 0x80000000, v46
	v_xor_b32_e32 v42, 0x80000000, v77
	v_pk_fma_f32 v[42:43], v[42:43], s[8:9], v[70:71] op_sel_hi:[1,0,1]
	v_add_u32_e32 v46, 0x2b00800, v82
	global_store_dwordx4 v46, v[50:53], s[36:37] sc1
	global_store_dwordx4 v46, v[42:45], s[36:37] offset:16 sc1
	v_pk_add_f32 v[28:29], v[28:29], v[60:61]
	v_pk_add_f32 v[32:33], v[32:33], v[64:65]
; __device__ __forceinline__ float logsigf(float x) { return fminf(x, 0.f) - 0.6931471805599453f * __builtin_amdgcn_logf(1.f + __builtin_amdgcn_exp2f(-1.4426950408889634f * fabsf(x))); }
;     __device__ __forceinline__ void operator()(const f32x4 (&acc)[2][2][4][2], const pg8::Unit& u, int wr, int wc, int fr, int fq) const {
;     ...
;                         for (int m = 0; m < 4; ++m) { const float r = rs[ai][m]; const f32x4 vi = acc[ai][0][m][0] * r + bv[0][0] + g0; f32x4 vf = acc[ai][0][m][1] * r + bv[0][1] + g1;
;                             vf = (f32x4){logsigf(vf[0]), logsigf(vf[1]), logsigf(vf[2]), logsigf(vf[3])};
;                             const unsigned go = (unsigned)WS_G + (rbase + ai * 128 + m * 16) * 64u + 32u * fq; stg_f4(wst, go, vi); stg_f4(wst, go + 16u, vf); } }
	v_mov_b32_e32 v42, v175
	v_pk_fma_f32 v[34:35], v[34:35], v[42:43], v[132:133] op_sel_hi:[1,0,1]
	v_pk_fma_f32 v[40:41], v[40:41], v[42:43], v[138:139] op_sel_hi:[1,0,1]
	v_pk_add_f32 v[34:35], v[34:35], v[58:59]
	v_pk_fma_f32 v[38:39], v[38:39], v[42:43], v[136:137] op_sel_hi:[1,0,1]
	v_mul_f32_e64 v43, |v34|, s4
	v_exp_f32_e32 v43, v43
	v_pk_add_f32 v[40:41], v[40:41], v[64:65]
	v_pk_add_f32 v[38:39], v[38:39], v[62:63]
	v_pk_add_f32 v[30:31], v[30:31], v[62:63]
	v_pk_fma_f32 v[36:37], v[36:37], v[42:43], v[134:135] op_sel_hi:[1,0,1]
	v_min_f32_e32 v42, 0, v34
	v_add_f32_e32 v34, 1.0, v43
	v_pk_add_f32 v[36:37], v[36:37], v[60:61]
	v_log_f32_e32 v44, v34
	v_mul_f32_e64 v34, |v35|, s4
	v_min_f32_e32 v43, 0, v35
	v_exp_f32_e32 v34, v34
	v_mul_f32_e64 v35, |v36|, s4
	v_mul_f32_e64 v45, |v37|, s4
	v_exp_f32_e32 v35, v35
	v_exp_f32_e32 v45, v45
	v_add_f32_e32 v34, 1.0, v34
	v_log_f32_e32 v46, v34
	v_add_f32_e32 v34, 1.0, v35
	v_add_f32_e32 v35, 1.0, v45
	v_log_f32_e32 v45, v35
	v_log_f32_e32 v47, v34
	v_min_f32_e32 v34, 0, v36
	v_min_f32_e32 v35, 0, v37
	v_xor_b32_e32 v37, 0x80000000, v45
	v_xor_b32_e32 v36, 0x80000000, v47
	v_pk_fma_f32 v[36:37], v[36:37], s[8:9], v[34:35] op_sel_hi:[1,0,1]
	v_xor_b32_e32 v35, 0x80000000, v46
	v_xor_b32_e32 v34, 0x80000000, v44
	v_pk_fma_f32 v[34:35], v[34:35], s[8:9], v[42:43] op_sel_hi:[1,0,1]
	v_add_u32_e32 v42, 0x2b00c00, v82
	global_store_dwordx4 v42, v[38:41], s[36:37] sc1
	global_store_dwordx4 v42, v[34:37], s[36:37] offset:16 sc1
	v_pk_add_f32 v[10:11], v[10:11], v[58:59]
	v_mul_f32_e64 v38, |v29|, s4
	v_mul_f32_e64 v34, |v26|, s4
	v_exp_f32_e32 v35, v34
	v_min_f32_e32 v34, 0, v26
	v_exp_f32_e32 v38, v38
	v_add_u32_e32 v36, 0x2b02000, v82
	v_add_f32_e32 v26, 1.0, v35
	v_log_f32_e32 v37, v26
	v_mul_f32_e64 v26, |v27|, s4
	v_min_f32_e32 v35, 0, v27
	v_exp_f32_e32 v26, v26
	v_mul_f32_e64 v27, |v28|, s4
	v_exp_f32_e32 v27, v27
	v_pk_add_f32 v[12:13], v[12:13], v[60:61]
	v_add_f32_e32 v26, 1.0, v26
	v_log_f32_e32 v39, v26
	v_add_f32_e32 v26, 1.0, v27
	v_add_f32_e32 v27, 1.0, v38
	v_log_f32_e32 v38, v27
	v_log_f32_e32 v40, v26
	v_min_f32_e32 v26, 0, v28
	v_min_f32_e32 v27, 0, v29
	v_xor_b32_e32 v29, 0x80000000, v38
	v_xor_b32_e32 v28, 0x80000000, v40
	v_pk_fma_f32 v[28:29], v[28:29], s[8:9], v[26:27] op_sel_hi:[1,0,1]
	v_xor_b32_e32 v27, 0x80000000, v39
	v_xor_b32_e32 v26, 0x80000000, v37
	v_pk_fma_f32 v[26:27], v[26:27], s[8:9], v[34:35] op_sel_hi:[1,0,1]
	global_store_dwordx4 v36, v[30:33], s[36:37] sc1
	global_store_dwordx4 v36, v[26:29], s[36:37] offset:16 sc1
	v_pk_add_f32 v[16:17], v[16:17], v[64:65]
	v_pk_add_f32 v[14:15], v[14:15], v[62:63]
	v_mov_b32_e32 v26, v173
	v_pk_fma_f32 v[18:19], v[18:19], v[26:27], v[132:133] op_sel_hi:[1,0,1]
	v_pk_fma_f32 v[24:25], v[24:25], v[26:27], v[138:139] op_sel_hi:[1,0,1]
	v_pk_add_f32 v[18:19], v[18:19], v[58:59]
	v_pk_fma_f32 v[22:23], v[22:23], v[26:27], v[136:137] op_sel_hi:[1,0,1]
	v_mul_f32_e64 v27, |v18|, s4
	v_exp_f32_e32 v27, v27
	v_pk_add_f32 v[24:25], v[24:25], v[64:65]
	v_pk_add_f32 v[22:23], v[22:23], v[62:63]
	v_pk_fma_f32 v[20:21], v[20:21], v[26:27], v[134:135] op_sel_hi:[1,0,1]
	v_min_f32_e32 v26, 0, v18
	v_add_f32_e32 v18, 1.0, v27
	v_pk_add_f32 v[20:21], v[20:21], v[60:61]
	v_log_f32_e32 v28, v18
	v_mul_f32_e64 v18, |v19|, s4
	v_min_f32_e32 v27, 0, v19
	v_exp_f32_e32 v18, v18
	v_mul_f32_e64 v19, |v20|, s4
	v_mul_f32_e64 v29, |v21|, s4
	v_exp_f32_e32 v19, v19
	v_exp_f32_e32 v29, v29
	v_add_f32_e32 v18, 1.0, v18
	v_log_f32_e32 v30, v18
	v_add_f32_e32 v18, 1.0, v19
	v_add_f32_e32 v19, 1.0, v29
	v_log_f32_e32 v29, v19
	v_log_f32_e32 v31, v18
	v_min_f32_e32 v18, 0, v20
	v_min_f32_e32 v19, 0, v21
	v_xor_b32_e32 v21, 0x80000000, v29
	v_xor_b32_e32 v20, 0x80000000, v31
	v_pk_fma_f32 v[20:21], v[20:21], s[8:9], v[18:19] op_sel_hi:[1,0,1]
	v_xor_b32_e32 v19, 0x80000000, v30
	v_xor_b32_e32 v18, 0x80000000, v28
	v_pk_fma_f32 v[18:19], v[18:19], s[8:9], v[26:27] op_sel_hi:[1,0,1]
	v_add_u32_e32 v26, 0x2b02400, v82
	global_store_dwordx4 v26, v[22:25], s[36:37] sc1
	global_store_dwordx4 v26, v[18:21], s[36:37] offset:16 sc1
	s_nop 1
	v_mul_f32_e64 v18, |v10|, s4
	v_exp_f32_e32 v19, v18
	v_min_f32_e32 v18, 0, v10
	v_mul_f32_e64 v21, |v13|, s4
	v_exp_f32_e32 v21, v21
	v_add_f32_e32 v10, 1.0, v19
	v_log_f32_e32 v20, v10
	v_mul_f32_e64 v10, |v11|, s4
	v_min_f32_e32 v19, 0, v11
	v_exp_f32_e32 v10, v10
	v_mul_f32_e64 v11, |v12|, s4
	v_exp_f32_e32 v11, v11
	v_add_f32_e32 v10, 1.0, v10
	v_log_f32_e32 v22, v10
	v_add_f32_e32 v10, 1.0, v11
	v_add_f32_e32 v11, 1.0, v21
	v_log_f32_e32 v21, v11
	v_log_f32_e32 v23, v10
	v_min_f32_e32 v10, 0, v12
	v_min_f32_e32 v11, 0, v13
	v_xor_b32_e32 v13, 0x80000000, v21
	v_xor_b32_e32 v12, 0x80000000, v23
	v_pk_fma_f32 v[12:13], v[12:13], s[8:9], v[10:11] op_sel_hi:[1,0,1]
	v_xor_b32_e32 v11, 0x80000000, v22
	v_xor_b32_e32 v10, 0x80000000, v20
	v_pk_fma_f32 v[10:11], v[10:11], s[8:9], v[18:19] op_sel_hi:[1,0,1]
	v_add_u32_e32 v18, 0x2b02800, v82
	global_store_dwordx4 v18, v[14:17], s[36:37] sc1
	global_store_dwordx4 v18, v[10:13], s[36:37] offset:16 sc1
	s_nop 1
	v_mov_b32_e32 v10, v171
	v_pk_fma_f32 v[2:3], v[2:3], v[10:11], v[132:133] op_sel_hi:[1,0,1]
	v_pk_fma_f32 v[8:9], v[8:9], v[10:11], v[138:139] op_sel_hi:[1,0,1]
	v_pk_add_f32 v[2:3], v[2:3], v[58:59]
	v_pk_fma_f32 v[6:7], v[6:7], v[10:11], v[136:137] op_sel_hi:[1,0,1]
	v_mul_f32_e64 v11, |v2|, s4
	v_exp_f32_e32 v11, v11
	v_pk_add_f32 v[8:9], v[8:9], v[64:65]
	v_pk_add_f32 v[6:7], v[6:7], v[62:63]
	v_pk_fma_f32 v[4:5], v[4:5], v[10:11], v[134:135] op_sel_hi:[1,0,1]
	v_min_f32_e32 v10, 0, v2
	v_add_f32_e32 v2, 1.0, v11
	v_pk_add_f32 v[4:5], v[4:5], v[60:61]
	v_log_f32_e32 v12, v2
	v_mul_f32_e64 v2, |v3|, s4
	v_min_f32_e32 v11, 0, v3
	v_exp_f32_e32 v2, v2
	v_mul_f32_e64 v3, |v4|, s4
	v_mul_f32_e64 v13, |v5|, s4
	v_exp_f32_e32 v3, v3
	v_exp_f32_e32 v13, v13
	v_add_f32_e32 v2, 1.0, v2
	v_log_f32_e32 v14, v2
	v_add_f32_e32 v2, 1.0, v3
	v_add_f32_e32 v3, 1.0, v13
	v_log_f32_e32 v13, v3
	v_log_f32_e32 v15, v2
	v_min_f32_e32 v2, 0, v4
	v_min_f32_e32 v3, 0, v5
	v_xor_b32_e32 v5, 0x80000000, v13
	v_xor_b32_e32 v4, 0x80000000, v15
	v_pk_fma_f32 v[4:5], v[4:5], s[8:9], v[2:3] op_sel_hi:[1,0,1]
	v_xor_b32_e32 v3, 0x80000000, v14
	v_xor_b32_e32 v2, 0x80000000, v12
	v_pk_fma_f32 v[2:3], v[2:3], s[8:9], v[10:11] op_sel_hi:[1,0,1]
	v_add_u32_e32 v10, 0x2b02c00, v82
	global_store_dwordx4 v10, v[6:9], s[36:37] sc1
	global_store_dwordx4 v10, v[2:5], s[36:37] offset:16 sc1
